# fused GEMM+LayerNorm phases: LayerNorm row loads at agent scope (sc1) instead of an L2 invalidate per item
# speedup vs baseline: 1.0104x; 1.0104x over previous
.LBB0_63:
	s_or_b64 exec, exec, s[22:23]
	v_ashrrev_i32_e32 v2, 3, v4
	v_and_b32_e32 v2, -8, v2
	v_and_b32_e32 v3, 64, v219
	v_lshl_add_u32 v2, v0, 6, v2
	v_xor_b32_e32 v0, 16, v219
	v_add_u32_e32 v3, 64, v3
	v_cmp_lt_i32_e32 vcc, v0, v3
	s_barrier
	s_nop 0
	v_cndmask_b32_e32 v0, v219, v0, vcc
	v_lshlrev_b32_e32 v42, 2, v0
	v_xor_b32_e32 v0, 32, v219
	v_cmp_lt_i32_e32 vcc, v0, v3
	v_ashrrev_i32_e32 v3, 31, v2
	s_nop 0
	v_cndmask_b32_e32 v0, v219, v0, vcc
	v_lshlrev_b32_e32 v43, 2, v0
	v_lshlrev_b32_e32 v0, 4, v4
	v_and_b32_e32 v0, 0x3f0, v0
	s_nop 0
	s_waitcnt vmcnt(0)
	v_lshl_add_u64 v[26:27], s[12:13], 0, v[0:1]
	v_lshl_add_u64 v[28:29], s[10:11], 0, v[0:1]
	v_lshlrev_b64 v[6:7], 11, v[2:3]
	v_and_b32_e32 v0, 63, v4
	v_lshlrev_b64 v[2:3], 12, v[2:3]
	v_lshl_or_b32 v6, v0, 3, v6
	v_lshl_or_b32 v2, v0, 4, v2
	v_lshl_add_u64 v[30:31], s[0:1], 0, v[6:7]
	v_lshl_add_u64 v[32:33], s[8:9], 0, v[2:3]
	s_mov_b64 s[22:23], 0
	s_movk_i32 s24, 0xfc00
	s_movk_i32 s25, 0xf800
	s_mov_b32 s26, 0x1f80000
	s_mov_b64 s[28:29], 0x2000
.LBB0_64:
	v_lshlrev_b32_e32 v212, 4, v219
	v_lshlrev_b32_e32 v214, 3, v219
	v_readfirstlane_b32 s42, v32
	v_readfirstlane_b32 s43, v33
	v_readfirstlane_b32 s66, v30
	v_readfirstlane_b32 s67, v31
	global_load_dwordx4 v[184:187], v[26:27], off offset:0
	global_load_dwordx4 v[188:191], v[26:27], off offset:1024
	global_load_dwordx4 v[192:195], v[26:27], off offset:2048
	global_load_dwordx4 v[196:199], v[26:27], off offset:3072
	global_load_dwordx4 v[200:203], v[28:29], off offset:0
	global_load_dwordx4 v[204:207], v[28:29], off offset:1024
	global_load_dwordx4 v[226:229], v[28:29], off offset:2048
	global_load_dwordx4 v[230:233], v[28:29], off offset:3072
	s_sub_u32 s42, s42, 0x1000
	s_subb_u32 s43, s43, 0
	global_load_dwordx4 v[2:5], v212, s[42:43] offset:0 sc1
	global_load_dwordx4 v[6:9], v212, s[42:43] offset:1024 sc1
	global_load_dwordx4 v[10:13], v212, s[42:43] offset:2048 sc1
	global_load_dwordx4 v[14:17], v212, s[42:43] offset:3072 sc1
	s_add_u32 s44, s42, 0x1000
	s_addc_u32 s45, s43, 0
	global_load_dwordx4 v[18:21], v212, s[44:45] offset:0 sc1
	global_load_dwordx4 v[22:25], v212, s[44:45] offset:1024 sc1
	global_load_dwordx4 v[34:37], v212, s[44:45] offset:2048 sc1
	global_load_dwordx4 v[38:41], v212, s[44:45] offset:3072 sc1
	s_add_u32 s46, s44, 0x1000
	s_addc_u32 s47, s45, 0
	global_load_dwordx4 v[44:47], v212, s[46:47] offset:0 sc1
	global_load_dwordx4 v[48:51], v212, s[46:47] offset:1024 sc1
	global_load_dwordx4 v[52:55], v212, s[46:47] offset:2048 sc1
	global_load_dwordx4 v[56:59], v212, s[46:47] offset:3072 sc1
	s_add_u32 s48, s46, 0x1000
	s_addc_u32 s49, s47, 0
	global_load_dwordx4 v[60:63], v212, s[48:49] offset:0 sc1
	global_load_dwordx4 v[64:67], v212, s[48:49] offset:1024 sc1
	global_load_dwordx4 v[94:97], v212, s[48:49] offset:2048 sc1
	global_load_dwordx4 v[98:101], v212, s[48:49] offset:3072 sc1
	s_add_u32 s50, s48, 0x1000
	s_addc_u32 s51, s49, 0
	global_load_dwordx4 v[102:105], v212, s[50:51] offset:0 sc1
	global_load_dwordx4 v[106:109], v212, s[50:51] offset:1024 sc1
	global_load_dwordx4 v[110:113], v212, s[50:51] offset:2048 sc1
	global_load_dwordx4 v[114:117], v212, s[50:51] offset:3072 sc1
	s_add_u32 s52, s50, 0x1000
	s_addc_u32 s53, s51, 0
	global_load_dwordx4 v[118:121], v212, s[52:53] offset:0 sc1
	global_load_dwordx4 v[122:125], v212, s[52:53] offset:1024 sc1
	global_load_dwordx4 v[144:147], v212, s[52:53] offset:2048 sc1
	global_load_dwordx4 v[148:151], v212, s[52:53] offset:3072 sc1
	s_add_u32 s62, s52, 0x1000
	s_addc_u32 s63, s53, 0
	global_load_dwordx4 v[152:155], v212, s[62:63] offset:0 sc1
	global_load_dwordx4 v[156:159], v212, s[62:63] offset:1024 sc1
	global_load_dwordx4 v[160:163], v212, s[62:63] offset:2048 sc1
	global_load_dwordx4 v[164:167], v212, s[62:63] offset:3072 sc1
	s_add_u32 s64, s62, 0x1000
	s_addc_u32 s65, s63, 0
	global_load_dwordx4 v[168:171], v212, s[64:65] offset:0 sc1
	global_load_dwordx4 v[172:175], v212, s[64:65] offset:1024 sc1
	global_load_dwordx4 v[176:179], v212, s[64:65] offset:2048 sc1
	global_load_dwordx4 v[180:183], v212, s[64:65] offset:3072 sc1
	s_add_u32 s66, s66, 0x1f80000
	s_addc_u32 s67, s67, 0
	s_add_u32 s68, s66, 0x1000
	s_addc_u32 s69, s67, 0
	s_add_u32 s70, s68, 0x1000
	s_addc_u32 s71, s69, 0
	s_add_u32 s72, s70, 0x1000
	s_addc_u32 s73, s71, 0
	s_waitcnt vmcnt(28)
	v_pk_add_f32 v[76:77], v[2:3], v[4:5]
	v_pk_add_f32 v[136:137], v[6:7], v[8:9]
	v_pk_add_f32 v[138:139], v[10:11], v[12:13]
	v_pk_add_f32 v[208:209], v[14:15], v[16:17]
	v_pk_add_f32 v[76:77], v[76:77], v[136:137]
	v_pk_add_f32 v[138:139], v[138:139], v[208:209]
	v_pk_add_f32 v[76:77], v[76:77], v[138:139]
	v_add_f32_e32 v131, v76, v77
	s_nop 1
	v_add_f32_dpp v131, v131, v131 quad_perm:[1,0,3,2] row_mask:0xf bank_mask:0xf bound_ctrl:1
	s_nop 1
	v_add_f32_dpp v131, v131, v131 quad_perm:[2,3,0,1] row_mask:0xf bank_mask:0xf bound_ctrl:1
	s_nop 1
	v_add_f32_dpp v131, v131, v131 row_half_mirror row_mask:0xf bank_mask:0xf bound_ctrl:1
	s_nop 1
	v_add_f32_dpp v131, v131, v131 row_mirror row_mask:0xf bank_mask:0xf bound_ctrl:1
	s_nop 1
	v_readlane_b32 s56, v131, 0
	v_readlane_b32 s57, v131, 16
	v_readlane_b32 s58, v131, 32
	v_readlane_b32 s59, v131, 48
	v_mov_b32_e32 v222, s57
	v_mov_b32_e32 v223, s59
	v_add_f32_e32 v222, s56, v222
	v_add_f32_e32 v223, s58, v223
	v_add_f32_e32 v131, v222, v223
	v_mul_f32_e32 v216, 0x3a800000, v131
	v_pk_add_f32 v[2:3], v[2:3], v[216:217] op_sel_hi:[1,0] neg_lo:[0,1] neg_hi:[0,1]
	v_pk_add_f32 v[4:5], v[4:5], v[216:217] op_sel_hi:[1,0] neg_lo:[0,1] neg_hi:[0,1]
	v_pk_add_f32 v[6:7], v[6:7], v[216:217] op_sel_hi:[1,0] neg_lo:[0,1] neg_hi:[0,1]
	v_pk_add_f32 v[8:9], v[8:9], v[216:217] op_sel_hi:[1,0] neg_lo:[0,1] neg_hi:[0,1]
	v_pk_add_f32 v[10:11], v[10:11], v[216:217] op_sel_hi:[1,0] neg_lo:[0,1] neg_hi:[0,1]
	v_pk_add_f32 v[12:13], v[12:13], v[216:217] op_sel_hi:[1,0] neg_lo:[0,1] neg_hi:[0,1]
	v_pk_add_f32 v[14:15], v[14:15], v[216:217] op_sel_hi:[1,0] neg_lo:[0,1] neg_hi:[0,1]
	v_pk_add_f32 v[16:17], v[16:17], v[216:217] op_sel_hi:[1,0] neg_lo:[0,1] neg_hi:[0,1]
	v_pk_mul_f32 v[76:77], v[2:3], v[2:3]
	v_pk_mul_f32 v[136:137], v[4:5], v[4:5]
	v_add_f32_e32 v133, v76, v77
	v_add_f32_e32 v133, v136, v133
	v_add_f32_e32 v133, v137, v133
	v_pk_mul_f32 v[76:77], v[6:7], v[6:7]
	v_pk_mul_f32 v[136:137], v[8:9], v[8:9]
	v_add_f32_e32 v133, v76, v133
	v_add_f32_e32 v133, v77, v133
	v_add_f32_e32 v133, v136, v133
	v_add_f32_e32 v133, v137, v133
	v_pk_mul_f32 v[76:77], v[10:11], v[10:11]
	v_pk_mul_f32 v[136:137], v[12:13], v[12:13]
	v_add_f32_e32 v133, v76, v133
	v_add_f32_e32 v133, v77, v133
	v_add_f32_e32 v133, v136, v133
	v_add_f32_e32 v133, v137, v133
	v_pk_mul_f32 v[76:77], v[14:15], v[14:15]
	v_pk_mul_f32 v[136:137], v[16:17], v[16:17]
	v_add_f32_e32 v133, v76, v133
	v_add_f32_e32 v133, v77, v133
	v_add_f32_e32 v133, v136, v133
	v_add_f32_e32 v133, v137, v133
	s_nop 1
	v_add_f32_dpp v133, v133, v133 quad_perm:[1,0,3,2] row_mask:0xf bank_mask:0xf bound_ctrl:1
	s_nop 1
	v_add_f32_dpp v133, v133, v133 quad_perm:[2,3,0,1] row_mask:0xf bank_mask:0xf bound_ctrl:1
	s_nop 1
	v_add_f32_dpp v133, v133, v133 row_half_mirror row_mask:0xf bank_mask:0xf bound_ctrl:1
	s_nop 1
	v_add_f32_dpp v133, v133, v133 row_mirror row_mask:0xf bank_mask:0xf bound_ctrl:1
	s_nop 1
	v_readlane_b32 s56, v133, 0
	v_readlane_b32 s57, v133, 16
	v_readlane_b32 s58, v133, 32
	v_readlane_b32 s59, v133, 48
	v_mov_b32_e32 v222, s57
	v_mov_b32_e32 v223, s59
	v_add_f32_e32 v222, s56, v222
	v_add_f32_e32 v223, s58, v223
	v_add_f32_e32 v133, v222, v223
	v_fmamk_f32 v133, v133, 0x3a800000, v215
	v_cmp_gt_f32_e32 vcc, s33, v133
	v_mul_f32_e32 v222, 0x4b800000, v133
	s_nop 0
	v_cndmask_b32_e32 v133, v133, v222, vcc
	v_rsq_f32_e32 v133, v133
	s_nop 0
	v_mul_f32_e32 v222, 0x45800000, v133
	v_cndmask_b32_e32 v220, v133, v222, vcc
	v_pk_mul_f32 v[2:3], v[2:3], v[220:221] op_sel_hi:[1,0]
	v_pk_mul_f32 v[4:5], v[4:5], v[220:221] op_sel_hi:[1,0]
	v_pk_mul_f32 v[6:7], v[6:7], v[220:221] op_sel_hi:[1,0]
	v_pk_mul_f32 v[8:9], v[8:9], v[220:221] op_sel_hi:[1,0]
	v_pk_mul_f32 v[10:11], v[10:11], v[220:221] op_sel_hi:[1,0]
	v_pk_mul_f32 v[12:13], v[12:13], v[220:221] op_sel_hi:[1,0]
	v_pk_mul_f32 v[14:15], v[14:15], v[220:221] op_sel_hi:[1,0]
	v_pk_mul_f32 v[16:17], v[16:17], v[220:221] op_sel_hi:[1,0]
	v_pk_fma_f32 v[2:3], v[184:185], v[2:3], v[200:201]
	v_pk_fma_f32 v[4:5], v[186:187], v[4:5], v[202:203]
	v_pk_fma_f32 v[6:7], v[188:189], v[6:7], v[204:205]
	v_pk_fma_f32 v[8:9], v[190:191], v[8:9], v[206:207]
	v_pk_fma_f32 v[10:11], v[192:193], v[10:11], v[226:227]
	v_pk_fma_f32 v[12:13], v[194:195], v[12:13], v[228:229]
	v_pk_fma_f32 v[14:15], v[196:197], v[14:15], v[230:231]
	v_pk_fma_f32 v[16:17], v[198:199], v[16:17], v[232:233]
	global_store_dwordx4 v212, v[2:5], s[42:43] offset:0
	global_store_dwordx4 v212, v[6:9], s[42:43] offset:1024
	global_store_dwordx4 v212, v[10:13], s[42:43] offset:2048
	global_store_dwordx4 v212, v[14:17], s[42:43] offset:3072
	v_cvt_pk_bf16_f32 v2, v2, v3
	v_cvt_pk_bf16_f32 v3, v4, v5
	v_cvt_pk_bf16_f32 v6, v6, v7
	v_cvt_pk_bf16_f32 v7, v8, v9
	v_cvt_pk_bf16_f32 v10, v10, v11
	v_cvt_pk_bf16_f32 v11, v12, v13
	v_cvt_pk_bf16_f32 v14, v14, v15
	v_cvt_pk_bf16_f32 v15, v16, v17
	global_store_dwordx2 v214, v[2:3], s[66:67] offset:0
	global_store_dwordx2 v214, v[6:7], s[66:67] offset:512
	global_store_dwordx2 v214, v[10:11], s[66:67] offset:1024
	global_store_dwordx2 v214, v[14:15], s[66:67] offset:1536
	s_waitcnt vmcnt(32)
	v_pk_add_f32 v[76:77], v[18:19], v[20:21]
	v_pk_add_f32 v[136:137], v[22:23], v[24:25]
	v_pk_add_f32 v[138:139], v[34:35], v[36:37]
	v_pk_add_f32 v[208:209], v[38:39], v[40:41]
	v_pk_add_f32 v[76:77], v[76:77], v[136:137]
	v_pk_add_f32 v[138:139], v[138:139], v[208:209]
	v_pk_add_f32 v[76:77], v[76:77], v[138:139]
	v_add_f32_e32 v131, v76, v77
	s_nop 1
	v_add_f32_dpp v131, v131, v131 quad_perm:[1,0,3,2] row_mask:0xf bank_mask:0xf bound_ctrl:1
	s_nop 1
	v_add_f32_dpp v131, v131, v131 quad_perm:[2,3,0,1] row_mask:0xf bank_mask:0xf bound_ctrl:1
	s_nop 1
	v_add_f32_dpp v131, v131, v131 row_half_mirror row_mask:0xf bank_mask:0xf bound_ctrl:1
	s_nop 1
	v_add_f32_dpp v131, v131, v131 row_mirror row_mask:0xf bank_mask:0xf bound_ctrl:1
	s_nop 1
	v_readlane_b32 s56, v131, 0
	v_readlane_b32 s57, v131, 16
	v_readlane_b32 s58, v131, 32
	v_readlane_b32 s59, v131, 48
	v_mov_b32_e32 v222, s57
	v_mov_b32_e32 v223, s59
	v_add_f32_e32 v222, s56, v222
	v_add_f32_e32 v223, s58, v223
	v_add_f32_e32 v131, v222, v223
	v_mul_f32_e32 v216, 0x3a800000, v131
	v_pk_add_f32 v[18:19], v[18:19], v[216:217] op_sel_hi:[1,0] neg_lo:[0,1] neg_hi:[0,1]
	v_pk_add_f32 v[20:21], v[20:21], v[216:217] op_sel_hi:[1,0] neg_lo:[0,1] neg_hi:[0,1]
	v_pk_add_f32 v[22:23], v[22:23], v[216:217] op_sel_hi:[1,0] neg_lo:[0,1] neg_hi:[0,1]
	v_pk_add_f32 v[24:25], v[24:25], v[216:217] op_sel_hi:[1,0] neg_lo:[0,1] neg_hi:[0,1]
	v_pk_add_f32 v[34:35], v[34:35], v[216:217] op_sel_hi:[1,0] neg_lo:[0,1] neg_hi:[0,1]
	v_pk_add_f32 v[36:37], v[36:37], v[216:217] op_sel_hi:[1,0] neg_lo:[0,1] neg_hi:[0,1]
	v_pk_add_f32 v[38:39], v[38:39], v[216:217] op_sel_hi:[1,0] neg_lo:[0,1] neg_hi:[0,1]
	v_pk_add_f32 v[40:41], v[40:41], v[216:217] op_sel_hi:[1,0] neg_lo:[0,1] neg_hi:[0,1]
	v_pk_mul_f32 v[76:77], v[18:19], v[18:19]
	v_pk_mul_f32 v[136:137], v[20:21], v[20:21]
	v_add_f32_e32 v133, v76, v77
	v_add_f32_e32 v133, v136, v133
	v_add_f32_e32 v133, v137, v133
	v_pk_mul_f32 v[76:77], v[22:23], v[22:23]
	v_pk_mul_f32 v[136:137], v[24:25], v[24:25]
	v_add_f32_e32 v133, v76, v133
	v_add_f32_e32 v133, v77, v133
	v_add_f32_e32 v133, v136, v133
	v_add_f32_e32 v133, v137, v133
	v_pk_mul_f32 v[76:77], v[34:35], v[34:35]
	v_pk_mul_f32 v[136:137], v[36:37], v[36:37]
	v_add_f32_e32 v133, v76, v133
	v_add_f32_e32 v133, v77, v133
	v_add_f32_e32 v133, v136, v133
	v_add_f32_e32 v133, v137, v133
	v_pk_mul_f32 v[76:77], v[38:39], v[38:39]
	v_pk_mul_f32 v[136:137], v[40:41], v[40:41]
	v_add_f32_e32 v133, v76, v133
	v_add_f32_e32 v133, v77, v133
	v_add_f32_e32 v133, v136, v133
	v_add_f32_e32 v133, v137, v133
	s_nop 1
	v_add_f32_dpp v133, v133, v133 quad_perm:[1,0,3,2] row_mask:0xf bank_mask:0xf bound_ctrl:1
	s_nop 1
	v_add_f32_dpp v133, v133, v133 quad_perm:[2,3,0,1] row_mask:0xf bank_mask:0xf bound_ctrl:1
	s_nop 1
	v_add_f32_dpp v133, v133, v133 row_half_mirror row_mask:0xf bank_mask:0xf bound_ctrl:1
	s_nop 1
	v_add_f32_dpp v133, v133, v133 row_mirror row_mask:0xf bank_mask:0xf bound_ctrl:1
	s_nop 1
	v_readlane_b32 s56, v133, 0
	v_readlane_b32 s57, v133, 16
	v_readlane_b32 s58, v133, 32
	v_readlane_b32 s59, v133, 48
	v_mov_b32_e32 v222, s57
	v_mov_b32_e32 v223, s59
	v_add_f32_e32 v222, s56, v222
	v_add_f32_e32 v223, s58, v223
	v_add_f32_e32 v133, v222, v223
	v_fmamk_f32 v133, v133, 0x3a800000, v215
	v_cmp_gt_f32_e32 vcc, s33, v133
	v_mul_f32_e32 v222, 0x4b800000, v133
	s_nop 0
	v_cndmask_b32_e32 v133, v133, v222, vcc
	v_rsq_f32_e32 v133, v133
	s_nop 0
	v_mul_f32_e32 v222, 0x45800000, v133
	v_cndmask_b32_e32 v220, v133, v222, vcc
	v_pk_mul_f32 v[18:19], v[18:19], v[220:221] op_sel_hi:[1,0]
	v_pk_mul_f32 v[20:21], v[20:21], v[220:221] op_sel_hi:[1,0]
	v_pk_mul_f32 v[22:23], v[22:23], v[220:221] op_sel_hi:[1,0]
	v_pk_mul_f32 v[24:25], v[24:25], v[220:221] op_sel_hi:[1,0]
	v_pk_mul_f32 v[34:35], v[34:35], v[220:221] op_sel_hi:[1,0]
	v_pk_mul_f32 v[36:37], v[36:37], v[220:221] op_sel_hi:[1,0]
	v_pk_mul_f32 v[38:39], v[38:39], v[220:221] op_sel_hi:[1,0]
	v_pk_mul_f32 v[40:41], v[40:41], v[220:221] op_sel_hi:[1,0]
	v_pk_fma_f32 v[18:19], v[184:185], v[18:19], v[200:201]
	v_pk_fma_f32 v[20:21], v[186:187], v[20:21], v[202:203]
	v_pk_fma_f32 v[22:23], v[188:189], v[22:23], v[204:205]
	v_pk_fma_f32 v[24:25], v[190:191], v[24:25], v[206:207]
	v_pk_fma_f32 v[34:35], v[192:193], v[34:35], v[226:227]
	v_pk_fma_f32 v[36:37], v[194:195], v[36:37], v[228:229]
	v_pk_fma_f32 v[38:39], v[196:197], v[38:39], v[230:231]
	v_pk_fma_f32 v[40:41], v[198:199], v[40:41], v[232:233]
	global_store_dwordx4 v212, v[18:21], s[44:45] offset:0
	global_store_dwordx4 v212, v[22:25], s[44:45] offset:1024
	global_store_dwordx4 v212, v[34:37], s[44:45] offset:2048
	global_store_dwordx4 v212, v[38:41], s[44:45] offset:3072
	v_cvt_pk_bf16_f32 v18, v18, v19
	v_cvt_pk_bf16_f32 v19, v20, v21
	v_cvt_pk_bf16_f32 v22, v22, v23
	v_cvt_pk_bf16_f32 v23, v24, v25
	v_cvt_pk_bf16_f32 v34, v34, v35
	v_cvt_pk_bf16_f32 v35, v36, v37
	v_cvt_pk_bf16_f32 v38, v38, v39
	v_cvt_pk_bf16_f32 v39, v40, v41
	global_store_dwordx2 v214, v[18:19], s[66:67] offset:2048
	global_store_dwordx2 v214, v[22:23], s[66:67] offset:2560
	global_store_dwordx2 v214, v[34:35], s[66:67] offset:3072
	global_store_dwordx2 v214, v[38:39], s[66:67] offset:3584
	s_waitcnt vmcnt(36)
	v_pk_add_f32 v[76:77], v[44:45], v[46:47]
	v_pk_add_f32 v[136:137], v[48:49], v[50:51]
	v_pk_add_f32 v[138:139], v[52:53], v[54:55]
	v_pk_add_f32 v[208:209], v[56:57], v[58:59]
	v_pk_add_f32 v[76:77], v[76:77], v[136:137]
	v_pk_add_f32 v[138:139], v[138:139], v[208:209]
	v_pk_add_f32 v[76:77], v[76:77], v[138:139]
	v_add_f32_e32 v131, v76, v77
	s_nop 1
	v_add_f32_dpp v131, v131, v131 quad_perm:[1,0,3,2] row_mask:0xf bank_mask:0xf bound_ctrl:1
	s_nop 1
	v_add_f32_dpp v131, v131, v131 quad_perm:[2,3,0,1] row_mask:0xf bank_mask:0xf bound_ctrl:1
	s_nop 1
	v_add_f32_dpp v131, v131, v131 row_half_mirror row_mask:0xf bank_mask:0xf bound_ctrl:1
	s_nop 1
	v_add_f32_dpp v131, v131, v131 row_mirror row_mask:0xf bank_mask:0xf bound_ctrl:1
	s_nop 1
	v_readlane_b32 s56, v131, 0
	v_readlane_b32 s57, v131, 16
	v_readlane_b32 s58, v131, 32
	v_readlane_b32 s59, v131, 48
	v_mov_b32_e32 v222, s57
	v_mov_b32_e32 v223, s59
	v_add_f32_e32 v222, s56, v222
	v_add_f32_e32 v223, s58, v223
	v_add_f32_e32 v131, v222, v223
	v_mul_f32_e32 v216, 0x3a800000, v131
	v_pk_add_f32 v[44:45], v[44:45], v[216:217] op_sel_hi:[1,0] neg_lo:[0,1] neg_hi:[0,1]
	v_pk_add_f32 v[46:47], v[46:47], v[216:217] op_sel_hi:[1,0] neg_lo:[0,1] neg_hi:[0,1]
	v_pk_add_f32 v[48:49], v[48:49], v[216:217] op_sel_hi:[1,0] neg_lo:[0,1] neg_hi:[0,1]
	v_pk_add_f32 v[50:51], v[50:51], v[216:217] op_sel_hi:[1,0] neg_lo:[0,1] neg_hi:[0,1]
	v_pk_add_f32 v[52:53], v[52:53], v[216:217] op_sel_hi:[1,0] neg_lo:[0,1] neg_hi:[0,1]
	v_pk_add_f32 v[54:55], v[54:55], v[216:217] op_sel_hi:[1,0] neg_lo:[0,1] neg_hi:[0,1]
	v_pk_add_f32 v[56:57], v[56:57], v[216:217] op_sel_hi:[1,0] neg_lo:[0,1] neg_hi:[0,1]
	v_pk_add_f32 v[58:59], v[58:59], v[216:217] op_sel_hi:[1,0] neg_lo:[0,1] neg_hi:[0,1]
	v_pk_mul_f32 v[76:77], v[44:45], v[44:45]
	v_pk_mul_f32 v[136:137], v[46:47], v[46:47]
	v_add_f32_e32 v133, v76, v77
	v_add_f32_e32 v133, v136, v133
	v_add_f32_e32 v133, v137, v133
	v_pk_mul_f32 v[76:77], v[48:49], v[48:49]
	v_pk_mul_f32 v[136:137], v[50:51], v[50:51]
	v_add_f32_e32 v133, v76, v133
	v_add_f32_e32 v133, v77, v133
	v_add_f32_e32 v133, v136, v133
	v_add_f32_e32 v133, v137, v133
	v_pk_mul_f32 v[76:77], v[52:53], v[52:53]
	v_pk_mul_f32 v[136:137], v[54:55], v[54:55]
	v_add_f32_e32 v133, v76, v133
	v_add_f32_e32 v133, v77, v133
	v_add_f32_e32 v133, v136, v133
	v_add_f32_e32 v133, v137, v133
	v_pk_mul_f32 v[76:77], v[56:57], v[56:57]
	v_pk_mul_f32 v[136:137], v[58:59], v[58:59]
	v_add_f32_e32 v133, v76, v133
	v_add_f32_e32 v133, v77, v133
	v_add_f32_e32 v133, v136, v133
	v_add_f32_e32 v133, v137, v133
	s_nop 1
	v_add_f32_dpp v133, v133, v133 quad_perm:[1,0,3,2] row_mask:0xf bank_mask:0xf bound_ctrl:1
	s_nop 1
	v_add_f32_dpp v133, v133, v133 quad_perm:[2,3,0,1] row_mask:0xf bank_mask:0xf bound_ctrl:1
	s_nop 1
	v_add_f32_dpp v133, v133, v133 row_half_mirror row_mask:0xf bank_mask:0xf bound_ctrl:1
	s_nop 1
	v_add_f32_dpp v133, v133, v133 row_mirror row_mask:0xf bank_mask:0xf bound_ctrl:1
	s_nop 1
	v_readlane_b32 s56, v133, 0
	v_readlane_b32 s57, v133, 16
	v_readlane_b32 s58, v133, 32
	v_readlane_b32 s59, v133, 48
	v_mov_b32_e32 v222, s57
	v_mov_b32_e32 v223, s59
	v_add_f32_e32 v222, s56, v222
	v_add_f32_e32 v223, s58, v223
	v_add_f32_e32 v133, v222, v223
	v_fmamk_f32 v133, v133, 0x3a800000, v215
	v_cmp_gt_f32_e32 vcc, s33, v133
	v_mul_f32_e32 v222, 0x4b800000, v133
	s_nop 0
	v_cndmask_b32_e32 v133, v133, v222, vcc
	v_rsq_f32_e32 v133, v133
	s_nop 0
	v_mul_f32_e32 v222, 0x45800000, v133
	v_cndmask_b32_e32 v220, v133, v222, vcc
	v_pk_mul_f32 v[44:45], v[44:45], v[220:221] op_sel_hi:[1,0]
	v_pk_mul_f32 v[46:47], v[46:47], v[220:221] op_sel_hi:[1,0]
	v_pk_mul_f32 v[48:49], v[48:49], v[220:221] op_sel_hi:[1,0]
	v_pk_mul_f32 v[50:51], v[50:51], v[220:221] op_sel_hi:[1,0]
	v_pk_mul_f32 v[52:53], v[52:53], v[220:221] op_sel_hi:[1,0]
	v_pk_mul_f32 v[54:55], v[54:55], v[220:221] op_sel_hi:[1,0]
	v_pk_mul_f32 v[56:57], v[56:57], v[220:221] op_sel_hi:[1,0]
	v_pk_mul_f32 v[58:59], v[58:59], v[220:221] op_sel_hi:[1,0]
	v_pk_fma_f32 v[44:45], v[184:185], v[44:45], v[200:201]
	v_pk_fma_f32 v[46:47], v[186:187], v[46:47], v[202:203]
	v_pk_fma_f32 v[48:49], v[188:189], v[48:49], v[204:205]
	v_pk_fma_f32 v[50:51], v[190:191], v[50:51], v[206:207]
	v_pk_fma_f32 v[52:53], v[192:193], v[52:53], v[226:227]
	v_pk_fma_f32 v[54:55], v[194:195], v[54:55], v[228:229]
	v_pk_fma_f32 v[56:57], v[196:197], v[56:57], v[230:231]
	v_pk_fma_f32 v[58:59], v[198:199], v[58:59], v[232:233]
	global_store_dwordx4 v212, v[44:47], s[46:47] offset:0
	global_store_dwordx4 v212, v[48:51], s[46:47] offset:1024
	global_store_dwordx4 v212, v[52:55], s[46:47] offset:2048
	global_store_dwordx4 v212, v[56:59], s[46:47] offset:3072
	v_cvt_pk_bf16_f32 v44, v44, v45
	v_cvt_pk_bf16_f32 v45, v46, v47
	v_cvt_pk_bf16_f32 v48, v48, v49
	v_cvt_pk_bf16_f32 v49, v50, v51
	v_cvt_pk_bf16_f32 v52, v52, v53
	v_cvt_pk_bf16_f32 v53, v54, v55
	v_cvt_pk_bf16_f32 v56, v56, v57
	v_cvt_pk_bf16_f32 v57, v58, v59
	global_store_dwordx2 v214, v[44:45], s[68:69] offset:0
	global_store_dwordx2 v214, v[48:49], s[68:69] offset:512
	global_store_dwordx2 v214, v[52:53], s[68:69] offset:1024
	global_store_dwordx2 v214, v[56:57], s[68:69] offset:1536
	s_waitcnt vmcnt(40)
	v_pk_add_f32 v[76:77], v[60:61], v[62:63]
	v_pk_add_f32 v[136:137], v[64:65], v[66:67]
	v_pk_add_f32 v[138:139], v[94:95], v[96:97]
	v_pk_add_f32 v[208:209], v[98:99], v[100:101]
	v_pk_add_f32 v[76:77], v[76:77], v[136:137]
	v_pk_add_f32 v[138:139], v[138:139], v[208:209]
	v_pk_add_f32 v[76:77], v[76:77], v[138:139]
	v_add_f32_e32 v131, v76, v77
	s_nop 1
	v_add_f32_dpp v131, v131, v131 quad_perm:[1,0,3,2] row_mask:0xf bank_mask:0xf bound_ctrl:1
	s_nop 1
	v_add_f32_dpp v131, v131, v131 quad_perm:[2,3,0,1] row_mask:0xf bank_mask:0xf bound_ctrl:1
	s_nop 1
	v_add_f32_dpp v131, v131, v131 row_half_mirror row_mask:0xf bank_mask:0xf bound_ctrl:1
	s_nop 1
	v_add_f32_dpp v131, v131, v131 row_mirror row_mask:0xf bank_mask:0xf bound_ctrl:1
	s_nop 1
	v_readlane_b32 s56, v131, 0
	v_readlane_b32 s57, v131, 16
	v_readlane_b32 s58, v131, 32
	v_readlane_b32 s59, v131, 48
	v_mov_b32_e32 v222, s57
	v_mov_b32_e32 v223, s59
	v_add_f32_e32 v222, s56, v222
	v_add_f32_e32 v223, s58, v223
	v_add_f32_e32 v131, v222, v223
	v_mul_f32_e32 v216, 0x3a800000, v131
	v_pk_add_f32 v[60:61], v[60:61], v[216:217] op_sel_hi:[1,0] neg_lo:[0,1] neg_hi:[0,1]
	v_pk_add_f32 v[62:63], v[62:63], v[216:217] op_sel_hi:[1,0] neg_lo:[0,1] neg_hi:[0,1]
	v_pk_add_f32 v[64:65], v[64:65], v[216:217] op_sel_hi:[1,0] neg_lo:[0,1] neg_hi:[0,1]
	v_pk_add_f32 v[66:67], v[66:67], v[216:217] op_sel_hi:[1,0] neg_lo:[0,1] neg_hi:[0,1]
	v_pk_add_f32 v[94:95], v[94:95], v[216:217] op_sel_hi:[1,0] neg_lo:[0,1] neg_hi:[0,1]
	v_pk_add_f32 v[96:97], v[96:97], v[216:217] op_sel_hi:[1,0] neg_lo:[0,1] neg_hi:[0,1]
	v_pk_add_f32 v[98:99], v[98:99], v[216:217] op_sel_hi:[1,0] neg_lo:[0,1] neg_hi:[0,1]
	v_pk_add_f32 v[100:101], v[100:101], v[216:217] op_sel_hi:[1,0] neg_lo:[0,1] neg_hi:[0,1]
	v_pk_mul_f32 v[76:77], v[60:61], v[60:61]
	v_pk_mul_f32 v[136:137], v[62:63], v[62:63]
	v_add_f32_e32 v133, v76, v77
	v_add_f32_e32 v133, v136, v133
	v_add_f32_e32 v133, v137, v133
	v_pk_mul_f32 v[76:77], v[64:65], v[64:65]
	v_pk_mul_f32 v[136:137], v[66:67], v[66:67]
	v_add_f32_e32 v133, v76, v133
	v_add_f32_e32 v133, v77, v133
	v_add_f32_e32 v133, v136, v133
	v_add_f32_e32 v133, v137, v133
	v_pk_mul_f32 v[76:77], v[94:95], v[94:95]
	v_pk_mul_f32 v[136:137], v[96:97], v[96:97]
	v_add_f32_e32 v133, v76, v133
	v_add_f32_e32 v133, v77, v133
	v_add_f32_e32 v133, v136, v133
	v_add_f32_e32 v133, v137, v133
	v_pk_mul_f32 v[76:77], v[98:99], v[98:99]
	v_pk_mul_f32 v[136:137], v[100:101], v[100:101]
	v_add_f32_e32 v133, v76, v133
	v_add_f32_e32 v133, v77, v133
	v_add_f32_e32 v133, v136, v133
	v_add_f32_e32 v133, v137, v133
	s_nop 1
	v_add_f32_dpp v133, v133, v133 quad_perm:[1,0,3,2] row_mask:0xf bank_mask:0xf bound_ctrl:1
	s_nop 1
	v_add_f32_dpp v133, v133, v133 quad_perm:[2,3,0,1] row_mask:0xf bank_mask:0xf bound_ctrl:1
	s_nop 1
	v_add_f32_dpp v133, v133, v133 row_half_mirror row_mask:0xf bank_mask:0xf bound_ctrl:1
	s_nop 1
	v_add_f32_dpp v133, v133, v133 row_mirror row_mask:0xf bank_mask:0xf bound_ctrl:1
	s_nop 1
	v_readlane_b32 s56, v133, 0
	v_readlane_b32 s57, v133, 16
	v_readlane_b32 s58, v133, 32
	v_readlane_b32 s59, v133, 48
	v_mov_b32_e32 v222, s57
	v_mov_b32_e32 v223, s59
	v_add_f32_e32 v222, s56, v222
	v_add_f32_e32 v223, s58, v223
	v_add_f32_e32 v133, v222, v223
	v_fmamk_f32 v133, v133, 0x3a800000, v215
	v_cmp_gt_f32_e32 vcc, s33, v133
	v_mul_f32_e32 v222, 0x4b800000, v133
	s_nop 0
	v_cndmask_b32_e32 v133, v133, v222, vcc
	v_rsq_f32_e32 v133, v133
	s_nop 0
	v_mul_f32_e32 v222, 0x45800000, v133
	v_cndmask_b32_e32 v220, v133, v222, vcc
	v_pk_mul_f32 v[60:61], v[60:61], v[220:221] op_sel_hi:[1,0]
	v_pk_mul_f32 v[62:63], v[62:63], v[220:221] op_sel_hi:[1,0]
	v_pk_mul_f32 v[64:65], v[64:65], v[220:221] op_sel_hi:[1,0]
	v_pk_mul_f32 v[66:67], v[66:67], v[220:221] op_sel_hi:[1,0]
	v_pk_mul_f32 v[94:95], v[94:95], v[220:221] op_sel_hi:[1,0]
	v_pk_mul_f32 v[96:97], v[96:97], v[220:221] op_sel_hi:[1,0]
	v_pk_mul_f32 v[98:99], v[98:99], v[220:221] op_sel_hi:[1,0]
	v_pk_mul_f32 v[100:101], v[100:101], v[220:221] op_sel_hi:[1,0]
	v_pk_fma_f32 v[60:61], v[184:185], v[60:61], v[200:201]
	v_pk_fma_f32 v[62:63], v[186:187], v[62:63], v[202:203]
	v_pk_fma_f32 v[64:65], v[188:189], v[64:65], v[204:205]
	v_pk_fma_f32 v[66:67], v[190:191], v[66:67], v[206:207]
	v_pk_fma_f32 v[94:95], v[192:193], v[94:95], v[226:227]
	v_pk_fma_f32 v[96:97], v[194:195], v[96:97], v[228:229]
	v_pk_fma_f32 v[98:99], v[196:197], v[98:99], v[230:231]
	v_pk_fma_f32 v[100:101], v[198:199], v[100:101], v[232:233]
	global_store_dwordx4 v212, v[60:63], s[48:49] offset:0
	global_store_dwordx4 v212, v[64:67], s[48:49] offset:1024
	global_store_dwordx4 v212, v[94:97], s[48:49] offset:2048
	global_store_dwordx4 v212, v[98:101], s[48:49] offset:3072
	v_cvt_pk_bf16_f32 v60, v60, v61
	v_cvt_pk_bf16_f32 v61, v62, v63
	v_cvt_pk_bf16_f32 v64, v64, v65
	v_cvt_pk_bf16_f32 v65, v66, v67
	v_cvt_pk_bf16_f32 v94, v94, v95
	v_cvt_pk_bf16_f32 v95, v96, v97
	v_cvt_pk_bf16_f32 v98, v98, v99
	v_cvt_pk_bf16_f32 v99, v100, v101
	global_store_dwordx2 v214, v[60:61], s[68:69] offset:2048
	global_store_dwordx2 v214, v[64:65], s[68:69] offset:2560
	global_store_dwordx2 v214, v[94:95], s[68:69] offset:3072
	global_store_dwordx2 v214, v[98:99], s[68:69] offset:3584
	s_waitcnt vmcnt(44)
	v_pk_add_f32 v[76:77], v[102:103], v[104:105]
	v_pk_add_f32 v[136:137], v[106:107], v[108:109]
	v_pk_add_f32 v[138:139], v[110:111], v[112:113]
	v_pk_add_f32 v[208:209], v[114:115], v[116:117]
	v_pk_add_f32 v[76:77], v[76:77], v[136:137]
	v_pk_add_f32 v[138:139], v[138:139], v[208:209]
	v_pk_add_f32 v[76:77], v[76:77], v[138:139]
	v_add_f32_e32 v131, v76, v77
	s_nop 1
	v_add_f32_dpp v131, v131, v131 quad_perm:[1,0,3,2] row_mask:0xf bank_mask:0xf bound_ctrl:1
	s_nop 1
	v_add_f32_dpp v131, v131, v131 quad_perm:[2,3,0,1] row_mask:0xf bank_mask:0xf bound_ctrl:1
	s_nop 1
	v_add_f32_dpp v131, v131, v131 row_half_mirror row_mask:0xf bank_mask:0xf bound_ctrl:1
	s_nop 1
	v_add_f32_dpp v131, v131, v131 row_mirror row_mask:0xf bank_mask:0xf bound_ctrl:1
	s_nop 1
	v_readlane_b32 s56, v131, 0
	v_readlane_b32 s57, v131, 16
	v_readlane_b32 s58, v131, 32
	v_readlane_b32 s59, v131, 48
	v_mov_b32_e32 v222, s57
	v_mov_b32_e32 v223, s59
	v_add_f32_e32 v222, s56, v222
	v_add_f32_e32 v223, s58, v223
	v_add_f32_e32 v131, v222, v223
	v_mul_f32_e32 v216, 0x3a800000, v131
	v_pk_add_f32 v[102:103], v[102:103], v[216:217] op_sel_hi:[1,0] neg_lo:[0,1] neg_hi:[0,1]
	v_pk_add_f32 v[104:105], v[104:105], v[216:217] op_sel_hi:[1,0] neg_lo:[0,1] neg_hi:[0,1]
	v_pk_add_f32 v[106:107], v[106:107], v[216:217] op_sel_hi:[1,0] neg_lo:[0,1] neg_hi:[0,1]
	v_pk_add_f32 v[108:109], v[108:109], v[216:217] op_sel_hi:[1,0] neg_lo:[0,1] neg_hi:[0,1]
	v_pk_add_f32 v[110:111], v[110:111], v[216:217] op_sel_hi:[1,0] neg_lo:[0,1] neg_hi:[0,1]
	v_pk_add_f32 v[112:113], v[112:113], v[216:217] op_sel_hi:[1,0] neg_lo:[0,1] neg_hi:[0,1]
	v_pk_add_f32 v[114:115], v[114:115], v[216:217] op_sel_hi:[1,0] neg_lo:[0,1] neg_hi:[0,1]
	v_pk_add_f32 v[116:117], v[116:117], v[216:217] op_sel_hi:[1,0] neg_lo:[0,1] neg_hi:[0,1]
	v_pk_mul_f32 v[76:77], v[102:103], v[102:103]
	v_pk_mul_f32 v[136:137], v[104:105], v[104:105]
	v_add_f32_e32 v133, v76, v77
	v_add_f32_e32 v133, v136, v133
	v_add_f32_e32 v133, v137, v133
	v_pk_mul_f32 v[76:77], v[106:107], v[106:107]
	v_pk_mul_f32 v[136:137], v[108:109], v[108:109]
	v_add_f32_e32 v133, v76, v133
	v_add_f32_e32 v133, v77, v133
	v_add_f32_e32 v133, v136, v133
	v_add_f32_e32 v133, v137, v133
	v_pk_mul_f32 v[76:77], v[110:111], v[110:111]
	v_pk_mul_f32 v[136:137], v[112:113], v[112:113]
	v_add_f32_e32 v133, v76, v133
	v_add_f32_e32 v133, v77, v133
	v_add_f32_e32 v133, v136, v133
	v_add_f32_e32 v133, v137, v133
	v_pk_mul_f32 v[76:77], v[114:115], v[114:115]
	v_pk_mul_f32 v[136:137], v[116:117], v[116:117]
	v_add_f32_e32 v133, v76, v133
	v_add_f32_e32 v133, v77, v133
	v_add_f32_e32 v133, v136, v133
	v_add_f32_e32 v133, v137, v133
	s_nop 1
	v_add_f32_dpp v133, v133, v133 quad_perm:[1,0,3,2] row_mask:0xf bank_mask:0xf bound_ctrl:1
	s_nop 1
	v_add_f32_dpp v133, v133, v133 quad_perm:[2,3,0,1] row_mask:0xf bank_mask:0xf bound_ctrl:1
	s_nop 1
	v_add_f32_dpp v133, v133, v133 row_half_mirror row_mask:0xf bank_mask:0xf bound_ctrl:1
	s_nop 1
	v_add_f32_dpp v133, v133, v133 row_mirror row_mask:0xf bank_mask:0xf bound_ctrl:1
	s_nop 1
	v_readlane_b32 s56, v133, 0
	v_readlane_b32 s57, v133, 16
	v_readlane_b32 s58, v133, 32
	v_readlane_b32 s59, v133, 48
	v_mov_b32_e32 v222, s57
	v_mov_b32_e32 v223, s59
	v_add_f32_e32 v222, s56, v222
	v_add_f32_e32 v223, s58, v223
	v_add_f32_e32 v133, v222, v223
	v_fmamk_f32 v133, v133, 0x3a800000, v215
	v_cmp_gt_f32_e32 vcc, s33, v133
	v_mul_f32_e32 v222, 0x4b800000, v133
	s_nop 0
	v_cndmask_b32_e32 v133, v133, v222, vcc
	v_rsq_f32_e32 v133, v133
	s_nop 0
	v_mul_f32_e32 v222, 0x45800000, v133
	v_cndmask_b32_e32 v220, v133, v222, vcc
	v_pk_mul_f32 v[102:103], v[102:103], v[220:221] op_sel_hi:[1,0]
	v_pk_mul_f32 v[104:105], v[104:105], v[220:221] op_sel_hi:[1,0]
	v_pk_mul_f32 v[106:107], v[106:107], v[220:221] op_sel_hi:[1,0]
	v_pk_mul_f32 v[108:109], v[108:109], v[220:221] op_sel_hi:[1,0]
	v_pk_mul_f32 v[110:111], v[110:111], v[220:221] op_sel_hi:[1,0]
	v_pk_mul_f32 v[112:113], v[112:113], v[220:221] op_sel_hi:[1,0]
	v_pk_mul_f32 v[114:115], v[114:115], v[220:221] op_sel_hi:[1,0]
	v_pk_mul_f32 v[116:117], v[116:117], v[220:221] op_sel_hi:[1,0]
	v_pk_fma_f32 v[102:103], v[184:185], v[102:103], v[200:201]
	v_pk_fma_f32 v[104:105], v[186:187], v[104:105], v[202:203]
	v_pk_fma_f32 v[106:107], v[188:189], v[106:107], v[204:205]
	v_pk_fma_f32 v[108:109], v[190:191], v[108:109], v[206:207]
	v_pk_fma_f32 v[110:111], v[192:193], v[110:111], v[226:227]
	v_pk_fma_f32 v[112:113], v[194:195], v[112:113], v[228:229]
	v_pk_fma_f32 v[114:115], v[196:197], v[114:115], v[230:231]
	v_pk_fma_f32 v[116:117], v[198:199], v[116:117], v[232:233]
	global_store_dwordx4 v212, v[102:105], s[50:51] offset:0
	global_store_dwordx4 v212, v[106:109], s[50:51] offset:1024
	global_store_dwordx4 v212, v[110:113], s[50:51] offset:2048
	global_store_dwordx4 v212, v[114:117], s[50:51] offset:3072
	v_cvt_pk_bf16_f32 v102, v102, v103
	v_cvt_pk_bf16_f32 v103, v104, v105
	v_cvt_pk_bf16_f32 v106, v106, v107
	v_cvt_pk_bf16_f32 v107, v108, v109
	v_cvt_pk_bf16_f32 v110, v110, v111
	v_cvt_pk_bf16_f32 v111, v112, v113
	v_cvt_pk_bf16_f32 v114, v114, v115
	v_cvt_pk_bf16_f32 v115, v116, v117
	global_store_dwordx2 v214, v[102:103], s[70:71] offset:0
	global_store_dwordx2 v214, v[106:107], s[70:71] offset:512
	global_store_dwordx2 v214, v[110:111], s[70:71] offset:1024
	global_store_dwordx2 v214, v[114:115], s[70:71] offset:1536
	s_waitcnt vmcnt(48)
	v_pk_add_f32 v[76:77], v[118:119], v[120:121]
	v_pk_add_f32 v[136:137], v[122:123], v[124:125]
	v_pk_add_f32 v[138:139], v[144:145], v[146:147]
	v_pk_add_f32 v[208:209], v[148:149], v[150:151]
	v_pk_add_f32 v[76:77], v[76:77], v[136:137]
	v_pk_add_f32 v[138:139], v[138:139], v[208:209]
	v_pk_add_f32 v[76:77], v[76:77], v[138:139]
	v_add_f32_e32 v131, v76, v77
	s_nop 1
	v_add_f32_dpp v131, v131, v131 quad_perm:[1,0,3,2] row_mask:0xf bank_mask:0xf bound_ctrl:1
	s_nop 1
	v_add_f32_dpp v131, v131, v131 quad_perm:[2,3,0,1] row_mask:0xf bank_mask:0xf bound_ctrl:1
	s_nop 1
	v_add_f32_dpp v131, v131, v131 row_half_mirror row_mask:0xf bank_mask:0xf bound_ctrl:1
	s_nop 1
	v_add_f32_dpp v131, v131, v131 row_mirror row_mask:0xf bank_mask:0xf bound_ctrl:1
	s_nop 1
	v_readlane_b32 s56, v131, 0
	v_readlane_b32 s57, v131, 16
	v_readlane_b32 s58, v131, 32
	v_readlane_b32 s59, v131, 48
	v_mov_b32_e32 v222, s57
	v_mov_b32_e32 v223, s59
	v_add_f32_e32 v222, s56, v222
	v_add_f32_e32 v223, s58, v223
	v_add_f32_e32 v131, v222, v223
	v_mul_f32_e32 v216, 0x3a800000, v131
	v_pk_add_f32 v[118:119], v[118:119], v[216:217] op_sel_hi:[1,0] neg_lo:[0,1] neg_hi:[0,1]
	v_pk_add_f32 v[120:121], v[120:121], v[216:217] op_sel_hi:[1,0] neg_lo:[0,1] neg_hi:[0,1]
	v_pk_add_f32 v[122:123], v[122:123], v[216:217] op_sel_hi:[1,0] neg_lo:[0,1] neg_hi:[0,1]
	v_pk_add_f32 v[124:125], v[124:125], v[216:217] op_sel_hi:[1,0] neg_lo:[0,1] neg_hi:[0,1]
	v_pk_add_f32 v[144:145], v[144:145], v[216:217] op_sel_hi:[1,0] neg_lo:[0,1] neg_hi:[0,1]
	v_pk_add_f32 v[146:147], v[146:147], v[216:217] op_sel_hi:[1,0] neg_lo:[0,1] neg_hi:[0,1]
	v_pk_add_f32 v[148:149], v[148:149], v[216:217] op_sel_hi:[1,0] neg_lo:[0,1] neg_hi:[0,1]
	v_pk_add_f32 v[150:151], v[150:151], v[216:217] op_sel_hi:[1,0] neg_lo:[0,1] neg_hi:[0,1]
	v_pk_mul_f32 v[76:77], v[118:119], v[118:119]
	v_pk_mul_f32 v[136:137], v[120:121], v[120:121]
	v_add_f32_e32 v133, v76, v77
	v_add_f32_e32 v133, v136, v133
	v_add_f32_e32 v133, v137, v133
	v_pk_mul_f32 v[76:77], v[122:123], v[122:123]
	v_pk_mul_f32 v[136:137], v[124:125], v[124:125]
	v_add_f32_e32 v133, v76, v133
	v_add_f32_e32 v133, v77, v133
	v_add_f32_e32 v133, v136, v133
	v_add_f32_e32 v133, v137, v133
	v_pk_mul_f32 v[76:77], v[144:145], v[144:145]
	v_pk_mul_f32 v[136:137], v[146:147], v[146:147]
	v_add_f32_e32 v133, v76, v133
	v_add_f32_e32 v133, v77, v133
	v_add_f32_e32 v133, v136, v133
	v_add_f32_e32 v133, v137, v133
	v_pk_mul_f32 v[76:77], v[148:149], v[148:149]
	v_pk_mul_f32 v[136:137], v[150:151], v[150:151]
	v_add_f32_e32 v133, v76, v133
	v_add_f32_e32 v133, v77, v133
	v_add_f32_e32 v133, v136, v133
	v_add_f32_e32 v133, v137, v133
	s_nop 1
	v_add_f32_dpp v133, v133, v133 quad_perm:[1,0,3,2] row_mask:0xf bank_mask:0xf bound_ctrl:1
	s_nop 1
	v_add_f32_dpp v133, v133, v133 quad_perm:[2,3,0,1] row_mask:0xf bank_mask:0xf bound_ctrl:1
	s_nop 1
	v_add_f32_dpp v133, v133, v133 row_half_mirror row_mask:0xf bank_mask:0xf bound_ctrl:1
	s_nop 1
	v_add_f32_dpp v133, v133, v133 row_mirror row_mask:0xf bank_mask:0xf bound_ctrl:1
	s_nop 1
	v_readlane_b32 s56, v133, 0
	v_readlane_b32 s57, v133, 16
	v_readlane_b32 s58, v133, 32
	v_readlane_b32 s59, v133, 48
	v_mov_b32_e32 v222, s57
	v_mov_b32_e32 v223, s59
	v_add_f32_e32 v222, s56, v222
	v_add_f32_e32 v223, s58, v223
	v_add_f32_e32 v133, v222, v223
	v_fmamk_f32 v133, v133, 0x3a800000, v215
	v_cmp_gt_f32_e32 vcc, s33, v133
	v_mul_f32_e32 v222, 0x4b800000, v133
	s_nop 0
	v_cndmask_b32_e32 v133, v133, v222, vcc
	v_rsq_f32_e32 v133, v133
	s_nop 0
	v_mul_f32_e32 v222, 0x45800000, v133
	v_cndmask_b32_e32 v220, v133, v222, vcc
	v_pk_mul_f32 v[118:119], v[118:119], v[220:221] op_sel_hi:[1,0]
	v_pk_mul_f32 v[120:121], v[120:121], v[220:221] op_sel_hi:[1,0]
	v_pk_mul_f32 v[122:123], v[122:123], v[220:221] op_sel_hi:[1,0]
	v_pk_mul_f32 v[124:125], v[124:125], v[220:221] op_sel_hi:[1,0]
	v_pk_mul_f32 v[144:145], v[144:145], v[220:221] op_sel_hi:[1,0]
	v_pk_mul_f32 v[146:147], v[146:147], v[220:221] op_sel_hi:[1,0]
	v_pk_mul_f32 v[148:149], v[148:149], v[220:221] op_sel_hi:[1,0]
	v_pk_mul_f32 v[150:151], v[150:151], v[220:221] op_sel_hi:[1,0]
	v_pk_fma_f32 v[118:119], v[184:185], v[118:119], v[200:201]
	v_pk_fma_f32 v[120:121], v[186:187], v[120:121], v[202:203]
	v_pk_fma_f32 v[122:123], v[188:189], v[122:123], v[204:205]
	v_pk_fma_f32 v[124:125], v[190:191], v[124:125], v[206:207]
	v_pk_fma_f32 v[144:145], v[192:193], v[144:145], v[226:227]
	v_pk_fma_f32 v[146:147], v[194:195], v[146:147], v[228:229]
	v_pk_fma_f32 v[148:149], v[196:197], v[148:149], v[230:231]
	v_pk_fma_f32 v[150:151], v[198:199], v[150:151], v[232:233]
	global_store_dwordx4 v212, v[118:121], s[52:53] offset:0
	global_store_dwordx4 v212, v[122:125], s[52:53] offset:1024
	global_store_dwordx4 v212, v[144:147], s[52:53] offset:2048
	global_store_dwordx4 v212, v[148:151], s[52:53] offset:3072
	v_cvt_pk_bf16_f32 v118, v118, v119
	v_cvt_pk_bf16_f32 v119, v120, v121
	v_cvt_pk_bf16_f32 v122, v122, v123
	v_cvt_pk_bf16_f32 v123, v124, v125
	v_cvt_pk_bf16_f32 v144, v144, v145
	v_cvt_pk_bf16_f32 v145, v146, v147
	v_cvt_pk_bf16_f32 v148, v148, v149
	v_cvt_pk_bf16_f32 v149, v150, v151
	global_store_dwordx2 v214, v[118:119], s[70:71] offset:2048
	global_store_dwordx2 v214, v[122:123], s[70:71] offset:2560
	global_store_dwordx2 v214, v[144:145], s[70:71] offset:3072
	global_store_dwordx2 v214, v[148:149], s[70:71] offset:3584
	s_waitcnt vmcnt(52)
	v_pk_add_f32 v[76:77], v[152:153], v[154:155]
	v_pk_add_f32 v[136:137], v[156:157], v[158:159]
	v_pk_add_f32 v[138:139], v[160:161], v[162:163]
	v_pk_add_f32 v[208:209], v[164:165], v[166:167]
	v_pk_add_f32 v[76:77], v[76:77], v[136:137]
	v_pk_add_f32 v[138:139], v[138:139], v[208:209]
	v_pk_add_f32 v[76:77], v[76:77], v[138:139]
	v_add_f32_e32 v131, v76, v77
	s_nop 1
	v_add_f32_dpp v131, v131, v131 quad_perm:[1,0,3,2] row_mask:0xf bank_mask:0xf bound_ctrl:1
	s_nop 1
	v_add_f32_dpp v131, v131, v131 quad_perm:[2,3,0,1] row_mask:0xf bank_mask:0xf bound_ctrl:1
	s_nop 1
	v_add_f32_dpp v131, v131, v131 row_half_mirror row_mask:0xf bank_mask:0xf bound_ctrl:1
	s_nop 1
	v_add_f32_dpp v131, v131, v131 row_mirror row_mask:0xf bank_mask:0xf bound_ctrl:1
	s_nop 1
	v_readlane_b32 s56, v131, 0
	v_readlane_b32 s57, v131, 16
	v_readlane_b32 s58, v131, 32
	v_readlane_b32 s59, v131, 48
	v_mov_b32_e32 v222, s57
	v_mov_b32_e32 v223, s59
	v_add_f32_e32 v222, s56, v222
	v_add_f32_e32 v223, s58, v223
	v_add_f32_e32 v131, v222, v223
	v_mul_f32_e32 v216, 0x3a800000, v131
	v_pk_add_f32 v[152:153], v[152:153], v[216:217] op_sel_hi:[1,0] neg_lo:[0,1] neg_hi:[0,1]
	v_pk_add_f32 v[154:155], v[154:155], v[216:217] op_sel_hi:[1,0] neg_lo:[0,1] neg_hi:[0,1]
	v_pk_add_f32 v[156:157], v[156:157], v[216:217] op_sel_hi:[1,0] neg_lo:[0,1] neg_hi:[0,1]
	v_pk_add_f32 v[158:159], v[158:159], v[216:217] op_sel_hi:[1,0] neg_lo:[0,1] neg_hi:[0,1]
	v_pk_add_f32 v[160:161], v[160:161], v[216:217] op_sel_hi:[1,0] neg_lo:[0,1] neg_hi:[0,1]
	v_pk_add_f32 v[162:163], v[162:163], v[216:217] op_sel_hi:[1,0] neg_lo:[0,1] neg_hi:[0,1]
	v_pk_add_f32 v[164:165], v[164:165], v[216:217] op_sel_hi:[1,0] neg_lo:[0,1] neg_hi:[0,1]
	v_pk_add_f32 v[166:167], v[166:167], v[216:217] op_sel_hi:[1,0] neg_lo:[0,1] neg_hi:[0,1]
	v_pk_mul_f32 v[76:77], v[152:153], v[152:153]
	v_pk_mul_f32 v[136:137], v[154:155], v[154:155]
	v_add_f32_e32 v133, v76, v77
	v_add_f32_e32 v133, v136, v133
	v_add_f32_e32 v133, v137, v133
	v_pk_mul_f32 v[76:77], v[156:157], v[156:157]
	v_pk_mul_f32 v[136:137], v[158:159], v[158:159]
	v_add_f32_e32 v133, v76, v133
	v_add_f32_e32 v133, v77, v133
	v_add_f32_e32 v133, v136, v133
	v_add_f32_e32 v133, v137, v133
	v_pk_mul_f32 v[76:77], v[160:161], v[160:161]
	v_pk_mul_f32 v[136:137], v[162:163], v[162:163]
	v_add_f32_e32 v133, v76, v133
	v_add_f32_e32 v133, v77, v133
	v_add_f32_e32 v133, v136, v133
	v_add_f32_e32 v133, v137, v133
	v_pk_mul_f32 v[76:77], v[164:165], v[164:165]
	v_pk_mul_f32 v[136:137], v[166:167], v[166:167]
	v_add_f32_e32 v133, v76, v133
	v_add_f32_e32 v133, v77, v133
	v_add_f32_e32 v133, v136, v133
	v_add_f32_e32 v133, v137, v133
	s_nop 1
	v_add_f32_dpp v133, v133, v133 quad_perm:[1,0,3,2] row_mask:0xf bank_mask:0xf bound_ctrl:1
	s_nop 1
	v_add_f32_dpp v133, v133, v133 quad_perm:[2,3,0,1] row_mask:0xf bank_mask:0xf bound_ctrl:1
	s_nop 1
	v_add_f32_dpp v133, v133, v133 row_half_mirror row_mask:0xf bank_mask:0xf bound_ctrl:1
	s_nop 1
	v_add_f32_dpp v133, v133, v133 row_mirror row_mask:0xf bank_mask:0xf bound_ctrl:1
	s_nop 1
	v_readlane_b32 s56, v133, 0
	v_readlane_b32 s57, v133, 16
	v_readlane_b32 s58, v133, 32
	v_readlane_b32 s59, v133, 48
	v_mov_b32_e32 v222, s57
	v_mov_b32_e32 v223, s59
	v_add_f32_e32 v222, s56, v222
	v_add_f32_e32 v223, s58, v223
	v_add_f32_e32 v133, v222, v223
	v_fmamk_f32 v133, v133, 0x3a800000, v215
	v_cmp_gt_f32_e32 vcc, s33, v133
	v_mul_f32_e32 v222, 0x4b800000, v133
	s_nop 0
	v_cndmask_b32_e32 v133, v133, v222, vcc
	v_rsq_f32_e32 v133, v133
	s_nop 0
	v_mul_f32_e32 v222, 0x45800000, v133
	v_cndmask_b32_e32 v220, v133, v222, vcc
	v_pk_mul_f32 v[152:153], v[152:153], v[220:221] op_sel_hi:[1,0]
	v_pk_mul_f32 v[154:155], v[154:155], v[220:221] op_sel_hi:[1,0]
	v_pk_mul_f32 v[156:157], v[156:157], v[220:221] op_sel_hi:[1,0]
	v_pk_mul_f32 v[158:159], v[158:159], v[220:221] op_sel_hi:[1,0]
	v_pk_mul_f32 v[160:161], v[160:161], v[220:221] op_sel_hi:[1,0]
	v_pk_mul_f32 v[162:163], v[162:163], v[220:221] op_sel_hi:[1,0]
	v_pk_mul_f32 v[164:165], v[164:165], v[220:221] op_sel_hi:[1,0]
	v_pk_mul_f32 v[166:167], v[166:167], v[220:221] op_sel_hi:[1,0]
	v_pk_fma_f32 v[152:153], v[184:185], v[152:153], v[200:201]
	v_pk_fma_f32 v[154:155], v[186:187], v[154:155], v[202:203]
	v_pk_fma_f32 v[156:157], v[188:189], v[156:157], v[204:205]
	v_pk_fma_f32 v[158:159], v[190:191], v[158:159], v[206:207]
	v_pk_fma_f32 v[160:161], v[192:193], v[160:161], v[226:227]
	v_pk_fma_f32 v[162:163], v[194:195], v[162:163], v[228:229]
	v_pk_fma_f32 v[164:165], v[196:197], v[164:165], v[230:231]
	v_pk_fma_f32 v[166:167], v[198:199], v[166:167], v[232:233]
	global_store_dwordx4 v212, v[152:155], s[62:63] offset:0
	global_store_dwordx4 v212, v[156:159], s[62:63] offset:1024
	global_store_dwordx4 v212, v[160:163], s[62:63] offset:2048
	global_store_dwordx4 v212, v[164:167], s[62:63] offset:3072
	v_cvt_pk_bf16_f32 v152, v152, v153
	v_cvt_pk_bf16_f32 v153, v154, v155
	v_cvt_pk_bf16_f32 v156, v156, v157
	v_cvt_pk_bf16_f32 v157, v158, v159
	v_cvt_pk_bf16_f32 v160, v160, v161
	v_cvt_pk_bf16_f32 v161, v162, v163
	v_cvt_pk_bf16_f32 v164, v164, v165
	v_cvt_pk_bf16_f32 v165, v166, v167
	global_store_dwordx2 v214, v[152:153], s[72:73] offset:0
	global_store_dwordx2 v214, v[156:157], s[72:73] offset:512
	global_store_dwordx2 v214, v[160:161], s[72:73] offset:1024
	global_store_dwordx2 v214, v[164:165], s[72:73] offset:1536
	s_waitcnt vmcnt(56)
	v_pk_add_f32 v[76:77], v[168:169], v[170:171]
	v_pk_add_f32 v[136:137], v[172:173], v[174:175]
	v_pk_add_f32 v[138:139], v[176:177], v[178:179]
	v_pk_add_f32 v[208:209], v[180:181], v[182:183]
	v_pk_add_f32 v[76:77], v[76:77], v[136:137]
	v_pk_add_f32 v[138:139], v[138:139], v[208:209]
	v_pk_add_f32 v[76:77], v[76:77], v[138:139]
	v_add_f32_e32 v131, v76, v77
	s_nop 1
	v_add_f32_dpp v131, v131, v131 quad_perm:[1,0,3,2] row_mask:0xf bank_mask:0xf bound_ctrl:1
	s_nop 1
	v_add_f32_dpp v131, v131, v131 quad_perm:[2,3,0,1] row_mask:0xf bank_mask:0xf bound_ctrl:1
	s_nop 1
	v_add_f32_dpp v131, v131, v131 row_half_mirror row_mask:0xf bank_mask:0xf bound_ctrl:1
	s_nop 1
	v_add_f32_dpp v131, v131, v131 row_mirror row_mask:0xf bank_mask:0xf bound_ctrl:1
	s_nop 1
	v_readlane_b32 s56, v131, 0
	v_readlane_b32 s57, v131, 16
	v_readlane_b32 s58, v131, 32
	v_readlane_b32 s59, v131, 48
	v_mov_b32_e32 v222, s57
	v_mov_b32_e32 v223, s59
	v_add_f32_e32 v222, s56, v222
	v_add_f32_e32 v223, s58, v223
	v_add_f32_e32 v131, v222, v223
	v_mul_f32_e32 v216, 0x3a800000, v131
	v_pk_add_f32 v[168:169], v[168:169], v[216:217] op_sel_hi:[1,0] neg_lo:[0,1] neg_hi:[0,1]
	v_pk_add_f32 v[170:171], v[170:171], v[216:217] op_sel_hi:[1,0] neg_lo:[0,1] neg_hi:[0,1]
	v_pk_add_f32 v[172:173], v[172:173], v[216:217] op_sel_hi:[1,0] neg_lo:[0,1] neg_hi:[0,1]
	v_pk_add_f32 v[174:175], v[174:175], v[216:217] op_sel_hi:[1,0] neg_lo:[0,1] neg_hi:[0,1]
	v_pk_add_f32 v[176:177], v[176:177], v[216:217] op_sel_hi:[1,0] neg_lo:[0,1] neg_hi:[0,1]
	v_pk_add_f32 v[178:179], v[178:179], v[216:217] op_sel_hi:[1,0] neg_lo:[0,1] neg_hi:[0,1]
	v_pk_add_f32 v[180:181], v[180:181], v[216:217] op_sel_hi:[1,0] neg_lo:[0,1] neg_hi:[0,1]
	v_pk_add_f32 v[182:183], v[182:183], v[216:217] op_sel_hi:[1,0] neg_lo:[0,1] neg_hi:[0,1]
	v_pk_mul_f32 v[76:77], v[168:169], v[168:169]
	v_pk_mul_f32 v[136:137], v[170:171], v[170:171]
	v_add_f32_e32 v133, v76, v77
	v_add_f32_e32 v133, v136, v133
	v_add_f32_e32 v133, v137, v133
	v_pk_mul_f32 v[76:77], v[172:173], v[172:173]
	v_pk_mul_f32 v[136:137], v[174:175], v[174:175]
	v_add_f32_e32 v133, v76, v133
	v_add_f32_e32 v133, v77, v133
	v_add_f32_e32 v133, v136, v133
	v_add_f32_e32 v133, v137, v133
	v_pk_mul_f32 v[76:77], v[176:177], v[176:177]
	v_pk_mul_f32 v[136:137], v[178:179], v[178:179]
	v_add_f32_e32 v133, v76, v133
	v_add_f32_e32 v133, v77, v133
	v_add_f32_e32 v133, v136, v133
	v_add_f32_e32 v133, v137, v133
	v_pk_mul_f32 v[76:77], v[180:181], v[180:181]
	v_pk_mul_f32 v[136:137], v[182:183], v[182:183]
	v_add_f32_e32 v133, v76, v133
	v_add_f32_e32 v133, v77, v133
	v_add_f32_e32 v133, v136, v133
	v_add_f32_e32 v133, v137, v133
	s_nop 1
	v_add_f32_dpp v133, v133, v133 quad_perm:[1,0,3,2] row_mask:0xf bank_mask:0xf bound_ctrl:1
	s_nop 1
	v_add_f32_dpp v133, v133, v133 quad_perm:[2,3,0,1] row_mask:0xf bank_mask:0xf bound_ctrl:1
	s_nop 1
	v_add_f32_dpp v133, v133, v133 row_half_mirror row_mask:0xf bank_mask:0xf bound_ctrl:1
	s_nop 1
	v_add_f32_dpp v133, v133, v133 row_mirror row_mask:0xf bank_mask:0xf bound_ctrl:1
	s_nop 1
	v_readlane_b32 s56, v133, 0
	v_readlane_b32 s57, v133, 16
	v_readlane_b32 s58, v133, 32
	v_readlane_b32 s59, v133, 48
	v_mov_b32_e32 v222, s57
	v_mov_b32_e32 v223, s59
	v_add_f32_e32 v222, s56, v222
	v_add_f32_e32 v223, s58, v223
	v_add_f32_e32 v133, v222, v223
	v_fmamk_f32 v133, v133, 0x3a800000, v215
	v_cmp_gt_f32_e32 vcc, s33, v133
	v_mul_f32_e32 v222, 0x4b800000, v133
	s_nop 0
	v_cndmask_b32_e32 v133, v133, v222, vcc
	v_rsq_f32_e32 v133, v133
	s_nop 0
	v_mul_f32_e32 v222, 0x45800000, v133
	v_cndmask_b32_e32 v220, v133, v222, vcc
	v_pk_mul_f32 v[168:169], v[168:169], v[220:221] op_sel_hi:[1,0]
	v_pk_mul_f32 v[170:171], v[170:171], v[220:221] op_sel_hi:[1,0]
	v_pk_mul_f32 v[172:173], v[172:173], v[220:221] op_sel_hi:[1,0]
	v_pk_mul_f32 v[174:175], v[174:175], v[220:221] op_sel_hi:[1,0]
	v_pk_mul_f32 v[176:177], v[176:177], v[220:221] op_sel_hi:[1,0]
	v_pk_mul_f32 v[178:179], v[178:179], v[220:221] op_sel_hi:[1,0]
	v_pk_mul_f32 v[180:181], v[180:181], v[220:221] op_sel_hi:[1,0]
	v_pk_mul_f32 v[182:183], v[182:183], v[220:221] op_sel_hi:[1,0]
	v_pk_fma_f32 v[168:169], v[184:185], v[168:169], v[200:201]
	v_pk_fma_f32 v[170:171], v[186:187], v[170:171], v[202:203]
	v_pk_fma_f32 v[172:173], v[188:189], v[172:173], v[204:205]
	v_pk_fma_f32 v[174:175], v[190:191], v[174:175], v[206:207]
	v_pk_fma_f32 v[176:177], v[192:193], v[176:177], v[226:227]
	v_pk_fma_f32 v[178:179], v[194:195], v[178:179], v[228:229]
	v_pk_fma_f32 v[180:181], v[196:197], v[180:181], v[230:231]
	v_pk_fma_f32 v[182:183], v[198:199], v[182:183], v[232:233]
	global_store_dwordx4 v212, v[168:171], s[64:65] offset:0
	global_store_dwordx4 v212, v[172:175], s[64:65] offset:1024
	global_store_dwordx4 v212, v[176:179], s[64:65] offset:2048
	global_store_dwordx4 v212, v[180:183], s[64:65] offset:3072
	v_cvt_pk_bf16_f32 v168, v168, v169
	v_cvt_pk_bf16_f32 v169, v170, v171
	v_cvt_pk_bf16_f32 v172, v172, v173
	v_cvt_pk_bf16_f32 v173, v174, v175
	v_cvt_pk_bf16_f32 v176, v176, v177
	v_cvt_pk_bf16_f32 v177, v178, v179
	v_cvt_pk_bf16_f32 v180, v180, v181
	v_cvt_pk_bf16_f32 v181, v182, v183
	global_store_dwordx2 v214, v[168:169], s[72:73] offset:2048
	global_store_dwordx2 v214, v[172:173], s[72:73] offset:2560
	global_store_dwordx2 v214, v[176:177], s[72:73] offset:3072
	global_store_dwordx2 v214, v[180:181], s[72:73] offset:3584
	s_xor_b64 s[22:23], exec, -1
	s_branch .LBB0_55

.LBB0_1617:
	s_or_b64 exec, exec, s[20:21]
	v_ashrrev_i32_e32 v2, 3, v4
	v_and_b32_e32 v2, -8, v2
	v_and_b32_e32 v3, 64, v219
	v_lshl_add_u32 v2, v0, 6, v2
	v_xor_b32_e32 v0, 16, v219
	v_add_u32_e32 v3, 64, v3
	v_cmp_lt_i32_e32 vcc, v0, v3
	s_barrier
	s_nop 0
	v_cndmask_b32_e32 v0, v219, v0, vcc
	v_lshlrev_b32_e32 v42, 2, v0
	v_xor_b32_e32 v0, 32, v219
	v_cmp_lt_i32_e32 vcc, v0, v3
	v_ashrrev_i32_e32 v3, 31, v2
	s_nop 0
	v_cndmask_b32_e32 v0, v219, v0, vcc
	v_lshlrev_b32_e32 v43, 2, v0
	v_lshlrev_b32_e32 v0, 4, v4
	v_and_b32_e32 v0, 0x3f0, v0
	s_nop 0
	s_waitcnt vmcnt(0)
	v_lshl_add_u64 v[26:27], s[8:9], 0, v[0:1]
	v_lshl_add_u64 v[28:29], s[10:11], 0, v[0:1]
	v_lshlrev_b64 v[6:7], 11, v[2:3]
	v_and_b32_e32 v0, 63, v4
	v_lshlrev_b64 v[2:3], 12, v[2:3]
	v_lshl_or_b32 v6, v0, 3, v6
	v_lshl_or_b32 v2, v0, 4, v2
	v_lshl_add_u64 v[30:31], s[0:1], 0, v[6:7]
	v_lshl_add_u64 v[32:33], s[4:5], 0, v[2:3]
	s_mov_b64 s[20:21], 0
	s_movk_i32 s22, 0xfc00
	s_movk_i32 s23, 0xf800
	s_mov_b32 s24, 0x1f80000
	s_mov_b64 s[26:27], 0x2000
.LBB0_1618:
	v_lshlrev_b32_e32 v212, 4, v219
	v_lshlrev_b32_e32 v214, 3, v219
	v_readfirstlane_b32 s42, v32
	v_readfirstlane_b32 s43, v33
	v_readfirstlane_b32 s66, v30
	v_readfirstlane_b32 s67, v31
	global_load_dwordx4 v[184:187], v[26:27], off offset:0
	global_load_dwordx4 v[188:191], v[26:27], off offset:1024
	global_load_dwordx4 v[192:195], v[26:27], off offset:2048
	global_load_dwordx4 v[196:199], v[26:27], off offset:3072
	global_load_dwordx4 v[200:203], v[28:29], off offset:0
	global_load_dwordx4 v[204:207], v[28:29], off offset:1024
	global_load_dwordx4 v[226:229], v[28:29], off offset:2048
	global_load_dwordx4 v[230:233], v[28:29], off offset:3072
	s_sub_u32 s42, s42, 0x1000
	s_subb_u32 s43, s43, 0
	global_load_dwordx4 v[2:5], v212, s[42:43] offset:0 sc1
	global_load_dwordx4 v[6:9], v212, s[42:43] offset:1024 sc1
	global_load_dwordx4 v[10:13], v212, s[42:43] offset:2048 sc1
	global_load_dwordx4 v[14:17], v212, s[42:43] offset:3072 sc1
	s_add_u32 s44, s42, 0x1000
	s_addc_u32 s45, s43, 0
	global_load_dwordx4 v[18:21], v212, s[44:45] offset:0 sc1
	global_load_dwordx4 v[22:25], v212, s[44:45] offset:1024 sc1
	global_load_dwordx4 v[34:37], v212, s[44:45] offset:2048 sc1
	global_load_dwordx4 v[38:41], v212, s[44:45] offset:3072 sc1
	s_add_u32 s46, s44, 0x1000
	s_addc_u32 s47, s45, 0
	global_load_dwordx4 v[44:47], v212, s[46:47] offset:0 sc1
	global_load_dwordx4 v[48:51], v212, s[46:47] offset:1024 sc1
	global_load_dwordx4 v[52:55], v212, s[46:47] offset:2048 sc1
	global_load_dwordx4 v[56:59], v212, s[46:47] offset:3072 sc1
	s_add_u32 s48, s46, 0x1000
	s_addc_u32 s49, s47, 0
	global_load_dwordx4 v[60:63], v212, s[48:49] offset:0 sc1
	global_load_dwordx4 v[64:67], v212, s[48:49] offset:1024 sc1
	global_load_dwordx4 v[94:97], v212, s[48:49] offset:2048 sc1
	global_load_dwordx4 v[98:101], v212, s[48:49] offset:3072 sc1
	s_add_u32 s50, s48, 0x1000
	s_addc_u32 s51, s49, 0
	global_load_dwordx4 v[102:105], v212, s[50:51] offset:0 sc1
	global_load_dwordx4 v[106:109], v212, s[50:51] offset:1024 sc1
	global_load_dwordx4 v[110:113], v212, s[50:51] offset:2048 sc1
	global_load_dwordx4 v[114:117], v212, s[50:51] offset:3072 sc1
	s_add_u32 s52, s50, 0x1000
	s_addc_u32 s53, s51, 0
	global_load_dwordx4 v[118:121], v212, s[52:53] offset:0 sc1
	global_load_dwordx4 v[122:125], v212, s[52:53] offset:1024 sc1
	global_load_dwordx4 v[144:147], v212, s[52:53] offset:2048 sc1
	global_load_dwordx4 v[148:151], v212, s[52:53] offset:3072 sc1
	s_add_u32 s62, s52, 0x1000
	s_addc_u32 s63, s53, 0
	global_load_dwordx4 v[152:155], v212, s[62:63] offset:0 sc1
	global_load_dwordx4 v[156:159], v212, s[62:63] offset:1024 sc1
	global_load_dwordx4 v[160:163], v212, s[62:63] offset:2048 sc1
	global_load_dwordx4 v[164:167], v212, s[62:63] offset:3072 sc1
	s_add_u32 s64, s62, 0x1000
	s_addc_u32 s65, s63, 0
	global_load_dwordx4 v[168:171], v212, s[64:65] offset:0 sc1
	global_load_dwordx4 v[172:175], v212, s[64:65] offset:1024 sc1
	global_load_dwordx4 v[176:179], v212, s[64:65] offset:2048 sc1
	global_load_dwordx4 v[180:183], v212, s[64:65] offset:3072 sc1
	s_add_u32 s66, s66, 0x1f80000
	s_addc_u32 s67, s67, 0
	s_add_u32 s68, s66, 0x1000
	s_addc_u32 s69, s67, 0
	s_add_u32 s70, s68, 0x1000
	s_addc_u32 s71, s69, 0
	s_add_u32 s72, s70, 0x1000
	s_addc_u32 s73, s71, 0
	s_waitcnt vmcnt(28)
	v_pk_add_f32 v[76:77], v[2:3], v[4:5]
	v_pk_add_f32 v[136:137], v[6:7], v[8:9]
	v_pk_add_f32 v[138:139], v[10:11], v[12:13]
	v_pk_add_f32 v[208:209], v[14:15], v[16:17]
	v_pk_add_f32 v[76:77], v[76:77], v[136:137]
	v_pk_add_f32 v[138:139], v[138:139], v[208:209]
	v_pk_add_f32 v[76:77], v[76:77], v[138:139]
	v_add_f32_e32 v131, v76, v77
	s_nop 1
	v_add_f32_dpp v131, v131, v131 quad_perm:[1,0,3,2] row_mask:0xf bank_mask:0xf bound_ctrl:1
	s_nop 1
	v_add_f32_dpp v131, v131, v131 quad_perm:[2,3,0,1] row_mask:0xf bank_mask:0xf bound_ctrl:1
	s_nop 1
	v_add_f32_dpp v131, v131, v131 row_half_mirror row_mask:0xf bank_mask:0xf bound_ctrl:1
	s_nop 1
	v_add_f32_dpp v131, v131, v131 row_mirror row_mask:0xf bank_mask:0xf bound_ctrl:1
	s_nop 1
	v_readlane_b32 s56, v131, 0
	v_readlane_b32 s57, v131, 16
	v_readlane_b32 s58, v131, 32
	v_readlane_b32 s59, v131, 48
	v_mov_b32_e32 v222, s57
	v_mov_b32_e32 v223, s59
	v_add_f32_e32 v222, s56, v222
	v_add_f32_e32 v223, s58, v223
	v_add_f32_e32 v131, v222, v223
	v_mul_f32_e32 v216, 0x3a800000, v131
	v_pk_add_f32 v[2:3], v[2:3], v[216:217] op_sel_hi:[1,0] neg_lo:[0,1] neg_hi:[0,1]
	v_pk_add_f32 v[4:5], v[4:5], v[216:217] op_sel_hi:[1,0] neg_lo:[0,1] neg_hi:[0,1]
	v_pk_add_f32 v[6:7], v[6:7], v[216:217] op_sel_hi:[1,0] neg_lo:[0,1] neg_hi:[0,1]
	v_pk_add_f32 v[8:9], v[8:9], v[216:217] op_sel_hi:[1,0] neg_lo:[0,1] neg_hi:[0,1]
	v_pk_add_f32 v[10:11], v[10:11], v[216:217] op_sel_hi:[1,0] neg_lo:[0,1] neg_hi:[0,1]
	v_pk_add_f32 v[12:13], v[12:13], v[216:217] op_sel_hi:[1,0] neg_lo:[0,1] neg_hi:[0,1]
	v_pk_add_f32 v[14:15], v[14:15], v[216:217] op_sel_hi:[1,0] neg_lo:[0,1] neg_hi:[0,1]
	v_pk_add_f32 v[16:17], v[16:17], v[216:217] op_sel_hi:[1,0] neg_lo:[0,1] neg_hi:[0,1]
	v_pk_mul_f32 v[76:77], v[2:3], v[2:3]
	v_pk_mul_f32 v[136:137], v[4:5], v[4:5]
	v_add_f32_e32 v133, v76, v77
	v_add_f32_e32 v133, v136, v133
	v_add_f32_e32 v133, v137, v133
	v_pk_mul_f32 v[76:77], v[6:7], v[6:7]
	v_pk_mul_f32 v[136:137], v[8:9], v[8:9]
	v_add_f32_e32 v133, v76, v133
	v_add_f32_e32 v133, v77, v133
	v_add_f32_e32 v133, v136, v133
	v_add_f32_e32 v133, v137, v133
	v_pk_mul_f32 v[76:77], v[10:11], v[10:11]
	v_pk_mul_f32 v[136:137], v[12:13], v[12:13]
	v_add_f32_e32 v133, v76, v133
	v_add_f32_e32 v133, v77, v133
	v_add_f32_e32 v133, v136, v133
	v_add_f32_e32 v133, v137, v133
	v_pk_mul_f32 v[76:77], v[14:15], v[14:15]
	v_pk_mul_f32 v[136:137], v[16:17], v[16:17]
	v_add_f32_e32 v133, v76, v133
	v_add_f32_e32 v133, v77, v133
	v_add_f32_e32 v133, v136, v133
	v_add_f32_e32 v133, v137, v133
	s_nop 1
	v_add_f32_dpp v133, v133, v133 quad_perm:[1,0,3,2] row_mask:0xf bank_mask:0xf bound_ctrl:1
	s_nop 1
	v_add_f32_dpp v133, v133, v133 quad_perm:[2,3,0,1] row_mask:0xf bank_mask:0xf bound_ctrl:1
	s_nop 1
	v_add_f32_dpp v133, v133, v133 row_half_mirror row_mask:0xf bank_mask:0xf bound_ctrl:1
	s_nop 1
	v_add_f32_dpp v133, v133, v133 row_mirror row_mask:0xf bank_mask:0xf bound_ctrl:1
	s_nop 1
	v_readlane_b32 s56, v133, 0
	v_readlane_b32 s57, v133, 16
	v_readlane_b32 s58, v133, 32
	v_readlane_b32 s59, v133, 48
	v_mov_b32_e32 v222, s57
	v_mov_b32_e32 v223, s59
	v_add_f32_e32 v222, s56, v222
	v_add_f32_e32 v223, s58, v223
	v_add_f32_e32 v133, v222, v223
	v_fmamk_f32 v133, v133, 0x3a800000, v215
	v_cmp_gt_f32_e32 vcc, s33, v133
	v_mul_f32_e32 v222, 0x4b800000, v133
	s_nop 0
	v_cndmask_b32_e32 v133, v133, v222, vcc
	v_rsq_f32_e32 v133, v133
	s_nop 0
	v_mul_f32_e32 v222, 0x45800000, v133
	v_cndmask_b32_e32 v220, v133, v222, vcc
	v_pk_mul_f32 v[2:3], v[2:3], v[220:221] op_sel_hi:[1,0]
	v_pk_mul_f32 v[4:5], v[4:5], v[220:221] op_sel_hi:[1,0]
	v_pk_mul_f32 v[6:7], v[6:7], v[220:221] op_sel_hi:[1,0]
	v_pk_mul_f32 v[8:9], v[8:9], v[220:221] op_sel_hi:[1,0]
	v_pk_mul_f32 v[10:11], v[10:11], v[220:221] op_sel_hi:[1,0]
	v_pk_mul_f32 v[12:13], v[12:13], v[220:221] op_sel_hi:[1,0]
	v_pk_mul_f32 v[14:15], v[14:15], v[220:221] op_sel_hi:[1,0]
	v_pk_mul_f32 v[16:17], v[16:17], v[220:221] op_sel_hi:[1,0]
	v_pk_fma_f32 v[2:3], v[184:185], v[2:3], v[200:201]
	v_pk_fma_f32 v[4:5], v[186:187], v[4:5], v[202:203]
	v_pk_fma_f32 v[6:7], v[188:189], v[6:7], v[204:205]
	v_pk_fma_f32 v[8:9], v[190:191], v[8:9], v[206:207]
	v_pk_fma_f32 v[10:11], v[192:193], v[10:11], v[226:227]
	v_pk_fma_f32 v[12:13], v[194:195], v[12:13], v[228:229]
	v_pk_fma_f32 v[14:15], v[196:197], v[14:15], v[230:231]
	v_pk_fma_f32 v[16:17], v[198:199], v[16:17], v[232:233]
	global_store_dwordx4 v212, v[2:5], s[42:43] offset:0
	global_store_dwordx4 v212, v[6:9], s[42:43] offset:1024
	global_store_dwordx4 v212, v[10:13], s[42:43] offset:2048
	global_store_dwordx4 v212, v[14:17], s[42:43] offset:3072
	v_cvt_pk_bf16_f32 v2, v2, v3
	v_cvt_pk_bf16_f32 v3, v4, v5
	v_cvt_pk_bf16_f32 v6, v6, v7
	v_cvt_pk_bf16_f32 v7, v8, v9
	v_cvt_pk_bf16_f32 v10, v10, v11
	v_cvt_pk_bf16_f32 v11, v12, v13
	v_cvt_pk_bf16_f32 v14, v14, v15
	v_cvt_pk_bf16_f32 v15, v16, v17
	global_store_dwordx2 v214, v[2:3], s[66:67] offset:0
	global_store_dwordx2 v214, v[6:7], s[66:67] offset:512
	global_store_dwordx2 v214, v[10:11], s[66:67] offset:1024
	global_store_dwordx2 v214, v[14:15], s[66:67] offset:1536
	s_waitcnt vmcnt(32)
	v_pk_add_f32 v[76:77], v[18:19], v[20:21]
	v_pk_add_f32 v[136:137], v[22:23], v[24:25]
	v_pk_add_f32 v[138:139], v[34:35], v[36:37]
	v_pk_add_f32 v[208:209], v[38:39], v[40:41]
	v_pk_add_f32 v[76:77], v[76:77], v[136:137]
	v_pk_add_f32 v[138:139], v[138:139], v[208:209]
	v_pk_add_f32 v[76:77], v[76:77], v[138:139]
	v_add_f32_e32 v131, v76, v77
	s_nop 1
	v_add_f32_dpp v131, v131, v131 quad_perm:[1,0,3,2] row_mask:0xf bank_mask:0xf bound_ctrl:1
	s_nop 1
	v_add_f32_dpp v131, v131, v131 quad_perm:[2,3,0,1] row_mask:0xf bank_mask:0xf bound_ctrl:1
	s_nop 1
	v_add_f32_dpp v131, v131, v131 row_half_mirror row_mask:0xf bank_mask:0xf bound_ctrl:1
	s_nop 1
	v_add_f32_dpp v131, v131, v131 row_mirror row_mask:0xf bank_mask:0xf bound_ctrl:1
	s_nop 1
	v_readlane_b32 s56, v131, 0
	v_readlane_b32 s57, v131, 16
	v_readlane_b32 s58, v131, 32
	v_readlane_b32 s59, v131, 48
	v_mov_b32_e32 v222, s57
	v_mov_b32_e32 v223, s59
	v_add_f32_e32 v222, s56, v222
	v_add_f32_e32 v223, s58, v223
	v_add_f32_e32 v131, v222, v223
	v_mul_f32_e32 v216, 0x3a800000, v131
	v_pk_add_f32 v[18:19], v[18:19], v[216:217] op_sel_hi:[1,0] neg_lo:[0,1] neg_hi:[0,1]
	v_pk_add_f32 v[20:21], v[20:21], v[216:217] op_sel_hi:[1,0] neg_lo:[0,1] neg_hi:[0,1]
	v_pk_add_f32 v[22:23], v[22:23], v[216:217] op_sel_hi:[1,0] neg_lo:[0,1] neg_hi:[0,1]
	v_pk_add_f32 v[24:25], v[24:25], v[216:217] op_sel_hi:[1,0] neg_lo:[0,1] neg_hi:[0,1]
	v_pk_add_f32 v[34:35], v[34:35], v[216:217] op_sel_hi:[1,0] neg_lo:[0,1] neg_hi:[0,1]
	v_pk_add_f32 v[36:37], v[36:37], v[216:217] op_sel_hi:[1,0] neg_lo:[0,1] neg_hi:[0,1]
	v_pk_add_f32 v[38:39], v[38:39], v[216:217] op_sel_hi:[1,0] neg_lo:[0,1] neg_hi:[0,1]
	v_pk_add_f32 v[40:41], v[40:41], v[216:217] op_sel_hi:[1,0] neg_lo:[0,1] neg_hi:[0,1]
	v_pk_mul_f32 v[76:77], v[18:19], v[18:19]
	v_pk_mul_f32 v[136:137], v[20:21], v[20:21]
	v_add_f32_e32 v133, v76, v77
	v_add_f32_e32 v133, v136, v133
	v_add_f32_e32 v133, v137, v133
	v_pk_mul_f32 v[76:77], v[22:23], v[22:23]
	v_pk_mul_f32 v[136:137], v[24:25], v[24:25]
	v_add_f32_e32 v133, v76, v133
	v_add_f32_e32 v133, v77, v133
	v_add_f32_e32 v133, v136, v133
	v_add_f32_e32 v133, v137, v133
	v_pk_mul_f32 v[76:77], v[34:35], v[34:35]
	v_pk_mul_f32 v[136:137], v[36:37], v[36:37]
	v_add_f32_e32 v133, v76, v133
	v_add_f32_e32 v133, v77, v133
	v_add_f32_e32 v133, v136, v133
	v_add_f32_e32 v133, v137, v133
	v_pk_mul_f32 v[76:77], v[38:39], v[38:39]
	v_pk_mul_f32 v[136:137], v[40:41], v[40:41]
	v_add_f32_e32 v133, v76, v133
	v_add_f32_e32 v133, v77, v133
	v_add_f32_e32 v133, v136, v133
	v_add_f32_e32 v133, v137, v133
	s_nop 1
	v_add_f32_dpp v133, v133, v133 quad_perm:[1,0,3,2] row_mask:0xf bank_mask:0xf bound_ctrl:1
	s_nop 1
	v_add_f32_dpp v133, v133, v133 quad_perm:[2,3,0,1] row_mask:0xf bank_mask:0xf bound_ctrl:1
	s_nop 1
	v_add_f32_dpp v133, v133, v133 row_half_mirror row_mask:0xf bank_mask:0xf bound_ctrl:1
	s_nop 1
	v_add_f32_dpp v133, v133, v133 row_mirror row_mask:0xf bank_mask:0xf bound_ctrl:1
	s_nop 1
	v_readlane_b32 s56, v133, 0
	v_readlane_b32 s57, v133, 16
	v_readlane_b32 s58, v133, 32
	v_readlane_b32 s59, v133, 48
	v_mov_b32_e32 v222, s57
	v_mov_b32_e32 v223, s59
	v_add_f32_e32 v222, s56, v222
	v_add_f32_e32 v223, s58, v223
	v_add_f32_e32 v133, v222, v223
	v_fmamk_f32 v133, v133, 0x3a800000, v215
	v_cmp_gt_f32_e32 vcc, s33, v133
	v_mul_f32_e32 v222, 0x4b800000, v133
	s_nop 0
	v_cndmask_b32_e32 v133, v133, v222, vcc
	v_rsq_f32_e32 v133, v133
	s_nop 0
	v_mul_f32_e32 v222, 0x45800000, v133
	v_cndmask_b32_e32 v220, v133, v222, vcc
	v_pk_mul_f32 v[18:19], v[18:19], v[220:221] op_sel_hi:[1,0]
	v_pk_mul_f32 v[20:21], v[20:21], v[220:221] op_sel_hi:[1,0]
	v_pk_mul_f32 v[22:23], v[22:23], v[220:221] op_sel_hi:[1,0]
	v_pk_mul_f32 v[24:25], v[24:25], v[220:221] op_sel_hi:[1,0]
	v_pk_mul_f32 v[34:35], v[34:35], v[220:221] op_sel_hi:[1,0]
	v_pk_mul_f32 v[36:37], v[36:37], v[220:221] op_sel_hi:[1,0]
	v_pk_mul_f32 v[38:39], v[38:39], v[220:221] op_sel_hi:[1,0]
	v_pk_mul_f32 v[40:41], v[40:41], v[220:221] op_sel_hi:[1,0]
	v_pk_fma_f32 v[18:19], v[184:185], v[18:19], v[200:201]
	v_pk_fma_f32 v[20:21], v[186:187], v[20:21], v[202:203]
	v_pk_fma_f32 v[22:23], v[188:189], v[22:23], v[204:205]
	v_pk_fma_f32 v[24:25], v[190:191], v[24:25], v[206:207]
	v_pk_fma_f32 v[34:35], v[192:193], v[34:35], v[226:227]
	v_pk_fma_f32 v[36:37], v[194:195], v[36:37], v[228:229]
	v_pk_fma_f32 v[38:39], v[196:197], v[38:39], v[230:231]
	v_pk_fma_f32 v[40:41], v[198:199], v[40:41], v[232:233]
	global_store_dwordx4 v212, v[18:21], s[44:45] offset:0
	global_store_dwordx4 v212, v[22:25], s[44:45] offset:1024
	global_store_dwordx4 v212, v[34:37], s[44:45] offset:2048
	global_store_dwordx4 v212, v[38:41], s[44:45] offset:3072
	v_cvt_pk_bf16_f32 v18, v18, v19
	v_cvt_pk_bf16_f32 v19, v20, v21
	v_cvt_pk_bf16_f32 v22, v22, v23
	v_cvt_pk_bf16_f32 v23, v24, v25
	v_cvt_pk_bf16_f32 v34, v34, v35
	v_cvt_pk_bf16_f32 v35, v36, v37
	v_cvt_pk_bf16_f32 v38, v38, v39
	v_cvt_pk_bf16_f32 v39, v40, v41
	global_store_dwordx2 v214, v[18:19], s[66:67] offset:2048
	global_store_dwordx2 v214, v[22:23], s[66:67] offset:2560
	global_store_dwordx2 v214, v[34:35], s[66:67] offset:3072
	global_store_dwordx2 v214, v[38:39], s[66:67] offset:3584
	s_waitcnt vmcnt(36)
	v_pk_add_f32 v[76:77], v[44:45], v[46:47]
	v_pk_add_f32 v[136:137], v[48:49], v[50:51]
	v_pk_add_f32 v[138:139], v[52:53], v[54:55]
	v_pk_add_f32 v[208:209], v[56:57], v[58:59]
	v_pk_add_f32 v[76:77], v[76:77], v[136:137]
	v_pk_add_f32 v[138:139], v[138:139], v[208:209]
	v_pk_add_f32 v[76:77], v[76:77], v[138:139]
	v_add_f32_e32 v131, v76, v77
	s_nop 1
	v_add_f32_dpp v131, v131, v131 quad_perm:[1,0,3,2] row_mask:0xf bank_mask:0xf bound_ctrl:1
	s_nop 1
	v_add_f32_dpp v131, v131, v131 quad_perm:[2,3,0,1] row_mask:0xf bank_mask:0xf bound_ctrl:1
	s_nop 1
	v_add_f32_dpp v131, v131, v131 row_half_mirror row_mask:0xf bank_mask:0xf bound_ctrl:1
	s_nop 1
	v_add_f32_dpp v131, v131, v131 row_mirror row_mask:0xf bank_mask:0xf bound_ctrl:1
	s_nop 1
	v_readlane_b32 s56, v131, 0
	v_readlane_b32 s57, v131, 16
	v_readlane_b32 s58, v131, 32
	v_readlane_b32 s59, v131, 48
	v_mov_b32_e32 v222, s57
	v_mov_b32_e32 v223, s59
	v_add_f32_e32 v222, s56, v222
	v_add_f32_e32 v223, s58, v223
	v_add_f32_e32 v131, v222, v223
	v_mul_f32_e32 v216, 0x3a800000, v131
	v_pk_add_f32 v[44:45], v[44:45], v[216:217] op_sel_hi:[1,0] neg_lo:[0,1] neg_hi:[0,1]
	v_pk_add_f32 v[46:47], v[46:47], v[216:217] op_sel_hi:[1,0] neg_lo:[0,1] neg_hi:[0,1]
	v_pk_add_f32 v[48:49], v[48:49], v[216:217] op_sel_hi:[1,0] neg_lo:[0,1] neg_hi:[0,1]
	v_pk_add_f32 v[50:51], v[50:51], v[216:217] op_sel_hi:[1,0] neg_lo:[0,1] neg_hi:[0,1]
	v_pk_add_f32 v[52:53], v[52:53], v[216:217] op_sel_hi:[1,0] neg_lo:[0,1] neg_hi:[0,1]
	v_pk_add_f32 v[54:55], v[54:55], v[216:217] op_sel_hi:[1,0] neg_lo:[0,1] neg_hi:[0,1]
	v_pk_add_f32 v[56:57], v[56:57], v[216:217] op_sel_hi:[1,0] neg_lo:[0,1] neg_hi:[0,1]
	v_pk_add_f32 v[58:59], v[58:59], v[216:217] op_sel_hi:[1,0] neg_lo:[0,1] neg_hi:[0,1]
	v_pk_mul_f32 v[76:77], v[44:45], v[44:45]
	v_pk_mul_f32 v[136:137], v[46:47], v[46:47]
	v_add_f32_e32 v133, v76, v77
	v_add_f32_e32 v133, v136, v133
	v_add_f32_e32 v133, v137, v133
	v_pk_mul_f32 v[76:77], v[48:49], v[48:49]
	v_pk_mul_f32 v[136:137], v[50:51], v[50:51]
	v_add_f32_e32 v133, v76, v133
	v_add_f32_e32 v133, v77, v133
	v_add_f32_e32 v133, v136, v133
	v_add_f32_e32 v133, v137, v133
	v_pk_mul_f32 v[76:77], v[52:53], v[52:53]
	v_pk_mul_f32 v[136:137], v[54:55], v[54:55]
	v_add_f32_e32 v133, v76, v133
	v_add_f32_e32 v133, v77, v133
	v_add_f32_e32 v133, v136, v133
	v_add_f32_e32 v133, v137, v133
	v_pk_mul_f32 v[76:77], v[56:57], v[56:57]
	v_pk_mul_f32 v[136:137], v[58:59], v[58:59]
	v_add_f32_e32 v133, v76, v133
	v_add_f32_e32 v133, v77, v133
	v_add_f32_e32 v133, v136, v133
	v_add_f32_e32 v133, v137, v133
	s_nop 1
	v_add_f32_dpp v133, v133, v133 quad_perm:[1,0,3,2] row_mask:0xf bank_mask:0xf bound_ctrl:1
	s_nop 1
	v_add_f32_dpp v133, v133, v133 quad_perm:[2,3,0,1] row_mask:0xf bank_mask:0xf bound_ctrl:1
	s_nop 1
	v_add_f32_dpp v133, v133, v133 row_half_mirror row_mask:0xf bank_mask:0xf bound_ctrl:1
	s_nop 1
	v_add_f32_dpp v133, v133, v133 row_mirror row_mask:0xf bank_mask:0xf bound_ctrl:1
	s_nop 1
	v_readlane_b32 s56, v133, 0
	v_readlane_b32 s57, v133, 16
	v_readlane_b32 s58, v133, 32
	v_readlane_b32 s59, v133, 48
	v_mov_b32_e32 v222, s57
	v_mov_b32_e32 v223, s59
	v_add_f32_e32 v222, s56, v222
	v_add_f32_e32 v223, s58, v223
	v_add_f32_e32 v133, v222, v223
	v_fmamk_f32 v133, v133, 0x3a800000, v215
	v_cmp_gt_f32_e32 vcc, s33, v133
	v_mul_f32_e32 v222, 0x4b800000, v133
	s_nop 0
	v_cndmask_b32_e32 v133, v133, v222, vcc
	v_rsq_f32_e32 v133, v133
	s_nop 0
	v_mul_f32_e32 v222, 0x45800000, v133
	v_cndmask_b32_e32 v220, v133, v222, vcc
	v_pk_mul_f32 v[44:45], v[44:45], v[220:221] op_sel_hi:[1,0]
	v_pk_mul_f32 v[46:47], v[46:47], v[220:221] op_sel_hi:[1,0]
	v_pk_mul_f32 v[48:49], v[48:49], v[220:221] op_sel_hi:[1,0]
	v_pk_mul_f32 v[50:51], v[50:51], v[220:221] op_sel_hi:[1,0]
	v_pk_mul_f32 v[52:53], v[52:53], v[220:221] op_sel_hi:[1,0]
	v_pk_mul_f32 v[54:55], v[54:55], v[220:221] op_sel_hi:[1,0]
	v_pk_mul_f32 v[56:57], v[56:57], v[220:221] op_sel_hi:[1,0]
	v_pk_mul_f32 v[58:59], v[58:59], v[220:221] op_sel_hi:[1,0]
	v_pk_fma_f32 v[44:45], v[184:185], v[44:45], v[200:201]
	v_pk_fma_f32 v[46:47], v[186:187], v[46:47], v[202:203]
	v_pk_fma_f32 v[48:49], v[188:189], v[48:49], v[204:205]
	v_pk_fma_f32 v[50:51], v[190:191], v[50:51], v[206:207]
	v_pk_fma_f32 v[52:53], v[192:193], v[52:53], v[226:227]
	v_pk_fma_f32 v[54:55], v[194:195], v[54:55], v[228:229]
	v_pk_fma_f32 v[56:57], v[196:197], v[56:57], v[230:231]
	v_pk_fma_f32 v[58:59], v[198:199], v[58:59], v[232:233]
	global_store_dwordx4 v212, v[44:47], s[46:47] offset:0
	global_store_dwordx4 v212, v[48:51], s[46:47] offset:1024
	global_store_dwordx4 v212, v[52:55], s[46:47] offset:2048
	global_store_dwordx4 v212, v[56:59], s[46:47] offset:3072
	v_cvt_pk_bf16_f32 v44, v44, v45
	v_cvt_pk_bf16_f32 v45, v46, v47
	v_cvt_pk_bf16_f32 v48, v48, v49
	v_cvt_pk_bf16_f32 v49, v50, v51
	v_cvt_pk_bf16_f32 v52, v52, v53
	v_cvt_pk_bf16_f32 v53, v54, v55
	v_cvt_pk_bf16_f32 v56, v56, v57
	v_cvt_pk_bf16_f32 v57, v58, v59
	global_store_dwordx2 v214, v[44:45], s[68:69] offset:0
	global_store_dwordx2 v214, v[48:49], s[68:69] offset:512
	global_store_dwordx2 v214, v[52:53], s[68:69] offset:1024
	global_store_dwordx2 v214, v[56:57], s[68:69] offset:1536
	s_waitcnt vmcnt(40)
	v_pk_add_f32 v[76:77], v[60:61], v[62:63]
	v_pk_add_f32 v[136:137], v[64:65], v[66:67]
	v_pk_add_f32 v[138:139], v[94:95], v[96:97]
	v_pk_add_f32 v[208:209], v[98:99], v[100:101]
	v_pk_add_f32 v[76:77], v[76:77], v[136:137]
	v_pk_add_f32 v[138:139], v[138:139], v[208:209]
	v_pk_add_f32 v[76:77], v[76:77], v[138:139]
	v_add_f32_e32 v131, v76, v77
	s_nop 1
	v_add_f32_dpp v131, v131, v131 quad_perm:[1,0,3,2] row_mask:0xf bank_mask:0xf bound_ctrl:1
	s_nop 1
	v_add_f32_dpp v131, v131, v131 quad_perm:[2,3,0,1] row_mask:0xf bank_mask:0xf bound_ctrl:1
	s_nop 1
	v_add_f32_dpp v131, v131, v131 row_half_mirror row_mask:0xf bank_mask:0xf bound_ctrl:1
	s_nop 1
	v_add_f32_dpp v131, v131, v131 row_mirror row_mask:0xf bank_mask:0xf bound_ctrl:1
	s_nop 1
	v_readlane_b32 s56, v131, 0
	v_readlane_b32 s57, v131, 16
	v_readlane_b32 s58, v131, 32
	v_readlane_b32 s59, v131, 48
	v_mov_b32_e32 v222, s57
	v_mov_b32_e32 v223, s59
	v_add_f32_e32 v222, s56, v222
	v_add_f32_e32 v223, s58, v223
	v_add_f32_e32 v131, v222, v223
	v_mul_f32_e32 v216, 0x3a800000, v131
	v_pk_add_f32 v[60:61], v[60:61], v[216:217] op_sel_hi:[1,0] neg_lo:[0,1] neg_hi:[0,1]
	v_pk_add_f32 v[62:63], v[62:63], v[216:217] op_sel_hi:[1,0] neg_lo:[0,1] neg_hi:[0,1]
	v_pk_add_f32 v[64:65], v[64:65], v[216:217] op_sel_hi:[1,0] neg_lo:[0,1] neg_hi:[0,1]
	v_pk_add_f32 v[66:67], v[66:67], v[216:217] op_sel_hi:[1,0] neg_lo:[0,1] neg_hi:[0,1]
	v_pk_add_f32 v[94:95], v[94:95], v[216:217] op_sel_hi:[1,0] neg_lo:[0,1] neg_hi:[0,1]
	v_pk_add_f32 v[96:97], v[96:97], v[216:217] op_sel_hi:[1,0] neg_lo:[0,1] neg_hi:[0,1]
	v_pk_add_f32 v[98:99], v[98:99], v[216:217] op_sel_hi:[1,0] neg_lo:[0,1] neg_hi:[0,1]
	v_pk_add_f32 v[100:101], v[100:101], v[216:217] op_sel_hi:[1,0] neg_lo:[0,1] neg_hi:[0,1]
	v_pk_mul_f32 v[76:77], v[60:61], v[60:61]
	v_pk_mul_f32 v[136:137], v[62:63], v[62:63]
	v_add_f32_e32 v133, v76, v77
	v_add_f32_e32 v133, v136, v133
	v_add_f32_e32 v133, v137, v133
	v_pk_mul_f32 v[76:77], v[64:65], v[64:65]
	v_pk_mul_f32 v[136:137], v[66:67], v[66:67]
	v_add_f32_e32 v133, v76, v133
	v_add_f32_e32 v133, v77, v133
	v_add_f32_e32 v133, v136, v133
	v_add_f32_e32 v133, v137, v133
	v_pk_mul_f32 v[76:77], v[94:95], v[94:95]
	v_pk_mul_f32 v[136:137], v[96:97], v[96:97]
	v_add_f32_e32 v133, v76, v133
	v_add_f32_e32 v133, v77, v133
	v_add_f32_e32 v133, v136, v133
	v_add_f32_e32 v133, v137, v133
	v_pk_mul_f32 v[76:77], v[98:99], v[98:99]
	v_pk_mul_f32 v[136:137], v[100:101], v[100:101]
	v_add_f32_e32 v133, v76, v133
	v_add_f32_e32 v133, v77, v133
	v_add_f32_e32 v133, v136, v133
	v_add_f32_e32 v133, v137, v133
	s_nop 1
	v_add_f32_dpp v133, v133, v133 quad_perm:[1,0,3,2] row_mask:0xf bank_mask:0xf bound_ctrl:1
	s_nop 1
	v_add_f32_dpp v133, v133, v133 quad_perm:[2,3,0,1] row_mask:0xf bank_mask:0xf bound_ctrl:1
	s_nop 1
	v_add_f32_dpp v133, v133, v133 row_half_mirror row_mask:0xf bank_mask:0xf bound_ctrl:1
	s_nop 1
	v_add_f32_dpp v133, v133, v133 row_mirror row_mask:0xf bank_mask:0xf bound_ctrl:1
	s_nop 1
	v_readlane_b32 s56, v133, 0
	v_readlane_b32 s57, v133, 16
	v_readlane_b32 s58, v133, 32
	v_readlane_b32 s59, v133, 48
	v_mov_b32_e32 v222, s57
	v_mov_b32_e32 v223, s59
	v_add_f32_e32 v222, s56, v222
	v_add_f32_e32 v223, s58, v223
	v_add_f32_e32 v133, v222, v223
	v_fmamk_f32 v133, v133, 0x3a800000, v215
	v_cmp_gt_f32_e32 vcc, s33, v133
	v_mul_f32_e32 v222, 0x4b800000, v133
	s_nop 0
	v_cndmask_b32_e32 v133, v133, v222, vcc
	v_rsq_f32_e32 v133, v133
	s_nop 0
	v_mul_f32_e32 v222, 0x45800000, v133
	v_cndmask_b32_e32 v220, v133, v222, vcc
	v_pk_mul_f32 v[60:61], v[60:61], v[220:221] op_sel_hi:[1,0]
	v_pk_mul_f32 v[62:63], v[62:63], v[220:221] op_sel_hi:[1,0]
	v_pk_mul_f32 v[64:65], v[64:65], v[220:221] op_sel_hi:[1,0]
	v_pk_mul_f32 v[66:67], v[66:67], v[220:221] op_sel_hi:[1,0]
	v_pk_mul_f32 v[94:95], v[94:95], v[220:221] op_sel_hi:[1,0]
	v_pk_mul_f32 v[96:97], v[96:97], v[220:221] op_sel_hi:[1,0]
	v_pk_mul_f32 v[98:99], v[98:99], v[220:221] op_sel_hi:[1,0]
	v_pk_mul_f32 v[100:101], v[100:101], v[220:221] op_sel_hi:[1,0]
	v_pk_fma_f32 v[60:61], v[184:185], v[60:61], v[200:201]
	v_pk_fma_f32 v[62:63], v[186:187], v[62:63], v[202:203]
	v_pk_fma_f32 v[64:65], v[188:189], v[64:65], v[204:205]
	v_pk_fma_f32 v[66:67], v[190:191], v[66:67], v[206:207]
	v_pk_fma_f32 v[94:95], v[192:193], v[94:95], v[226:227]
	v_pk_fma_f32 v[96:97], v[194:195], v[96:97], v[228:229]
	v_pk_fma_f32 v[98:99], v[196:197], v[98:99], v[230:231]
	v_pk_fma_f32 v[100:101], v[198:199], v[100:101], v[232:233]
	global_store_dwordx4 v212, v[60:63], s[48:49] offset:0
	global_store_dwordx4 v212, v[64:67], s[48:49] offset:1024
	global_store_dwordx4 v212, v[94:97], s[48:49] offset:2048
	global_store_dwordx4 v212, v[98:101], s[48:49] offset:3072
	v_cvt_pk_bf16_f32 v60, v60, v61
	v_cvt_pk_bf16_f32 v61, v62, v63
	v_cvt_pk_bf16_f32 v64, v64, v65
	v_cvt_pk_bf16_f32 v65, v66, v67
	v_cvt_pk_bf16_f32 v94, v94, v95
	v_cvt_pk_bf16_f32 v95, v96, v97
	v_cvt_pk_bf16_f32 v98, v98, v99
	v_cvt_pk_bf16_f32 v99, v100, v101
	global_store_dwordx2 v214, v[60:61], s[68:69] offset:2048
	global_store_dwordx2 v214, v[64:65], s[68:69] offset:2560
	global_store_dwordx2 v214, v[94:95], s[68:69] offset:3072
	global_store_dwordx2 v214, v[98:99], s[68:69] offset:3584
	s_waitcnt vmcnt(44)
	v_pk_add_f32 v[76:77], v[102:103], v[104:105]
	v_pk_add_f32 v[136:137], v[106:107], v[108:109]
	v_pk_add_f32 v[138:139], v[110:111], v[112:113]
	v_pk_add_f32 v[208:209], v[114:115], v[116:117]
	v_pk_add_f32 v[76:77], v[76:77], v[136:137]
	v_pk_add_f32 v[138:139], v[138:139], v[208:209]
	v_pk_add_f32 v[76:77], v[76:77], v[138:139]
	v_add_f32_e32 v131, v76, v77
	s_nop 1
	v_add_f32_dpp v131, v131, v131 quad_perm:[1,0,3,2] row_mask:0xf bank_mask:0xf bound_ctrl:1
	s_nop 1
	v_add_f32_dpp v131, v131, v131 quad_perm:[2,3,0,1] row_mask:0xf bank_mask:0xf bound_ctrl:1
	s_nop 1
	v_add_f32_dpp v131, v131, v131 row_half_mirror row_mask:0xf bank_mask:0xf bound_ctrl:1
	s_nop 1
	v_add_f32_dpp v131, v131, v131 row_mirror row_mask:0xf bank_mask:0xf bound_ctrl:1
	s_nop 1
	v_readlane_b32 s56, v131, 0
	v_readlane_b32 s57, v131, 16
	v_readlane_b32 s58, v131, 32
	v_readlane_b32 s59, v131, 48
	v_mov_b32_e32 v222, s57
	v_mov_b32_e32 v223, s59
	v_add_f32_e32 v222, s56, v222
	v_add_f32_e32 v223, s58, v223
	v_add_f32_e32 v131, v222, v223
	v_mul_f32_e32 v216, 0x3a800000, v131
	v_pk_add_f32 v[102:103], v[102:103], v[216:217] op_sel_hi:[1,0] neg_lo:[0,1] neg_hi:[0,1]
	v_pk_add_f32 v[104:105], v[104:105], v[216:217] op_sel_hi:[1,0] neg_lo:[0,1] neg_hi:[0,1]
	v_pk_add_f32 v[106:107], v[106:107], v[216:217] op_sel_hi:[1,0] neg_lo:[0,1] neg_hi:[0,1]
	v_pk_add_f32 v[108:109], v[108:109], v[216:217] op_sel_hi:[1,0] neg_lo:[0,1] neg_hi:[0,1]
	v_pk_add_f32 v[110:111], v[110:111], v[216:217] op_sel_hi:[1,0] neg_lo:[0,1] neg_hi:[0,1]
	v_pk_add_f32 v[112:113], v[112:113], v[216:217] op_sel_hi:[1,0] neg_lo:[0,1] neg_hi:[0,1]
	v_pk_add_f32 v[114:115], v[114:115], v[216:217] op_sel_hi:[1,0] neg_lo:[0,1] neg_hi:[0,1]
	v_pk_add_f32 v[116:117], v[116:117], v[216:217] op_sel_hi:[1,0] neg_lo:[0,1] neg_hi:[0,1]
	v_pk_mul_f32 v[76:77], v[102:103], v[102:103]
	v_pk_mul_f32 v[136:137], v[104:105], v[104:105]
	v_add_f32_e32 v133, v76, v77
	v_add_f32_e32 v133, v136, v133
	v_add_f32_e32 v133, v137, v133
	v_pk_mul_f32 v[76:77], v[106:107], v[106:107]
	v_pk_mul_f32 v[136:137], v[108:109], v[108:109]
	v_add_f32_e32 v133, v76, v133
	v_add_f32_e32 v133, v77, v133
	v_add_f32_e32 v133, v136, v133
	v_add_f32_e32 v133, v137, v133
	v_pk_mul_f32 v[76:77], v[110:111], v[110:111]
	v_pk_mul_f32 v[136:137], v[112:113], v[112:113]
	v_add_f32_e32 v133, v76, v133
	v_add_f32_e32 v133, v77, v133
	v_add_f32_e32 v133, v136, v133
	v_add_f32_e32 v133, v137, v133
	v_pk_mul_f32 v[76:77], v[114:115], v[114:115]
	v_pk_mul_f32 v[136:137], v[116:117], v[116:117]
	v_add_f32_e32 v133, v76, v133
	v_add_f32_e32 v133, v77, v133
	v_add_f32_e32 v133, v136, v133
	v_add_f32_e32 v133, v137, v133
	s_nop 1
	v_add_f32_dpp v133, v133, v133 quad_perm:[1,0,3,2] row_mask:0xf bank_mask:0xf bound_ctrl:1
	s_nop 1
	v_add_f32_dpp v133, v133, v133 quad_perm:[2,3,0,1] row_mask:0xf bank_mask:0xf bound_ctrl:1
	s_nop 1
	v_add_f32_dpp v133, v133, v133 row_half_mirror row_mask:0xf bank_mask:0xf bound_ctrl:1
	s_nop 1
	v_add_f32_dpp v133, v133, v133 row_mirror row_mask:0xf bank_mask:0xf bound_ctrl:1
	s_nop 1
	v_readlane_b32 s56, v133, 0
	v_readlane_b32 s57, v133, 16
	v_readlane_b32 s58, v133, 32
	v_readlane_b32 s59, v133, 48
	v_mov_b32_e32 v222, s57
	v_mov_b32_e32 v223, s59
	v_add_f32_e32 v222, s56, v222
	v_add_f32_e32 v223, s58, v223
	v_add_f32_e32 v133, v222, v223
	v_fmamk_f32 v133, v133, 0x3a800000, v215
	v_cmp_gt_f32_e32 vcc, s33, v133
	v_mul_f32_e32 v222, 0x4b800000, v133
	s_nop 0
	v_cndmask_b32_e32 v133, v133, v222, vcc
	v_rsq_f32_e32 v133, v133
	s_nop 0
	v_mul_f32_e32 v222, 0x45800000, v133
	v_cndmask_b32_e32 v220, v133, v222, vcc
	v_pk_mul_f32 v[102:103], v[102:103], v[220:221] op_sel_hi:[1,0]
	v_pk_mul_f32 v[104:105], v[104:105], v[220:221] op_sel_hi:[1,0]
	v_pk_mul_f32 v[106:107], v[106:107], v[220:221] op_sel_hi:[1,0]
	v_pk_mul_f32 v[108:109], v[108:109], v[220:221] op_sel_hi:[1,0]
	v_pk_mul_f32 v[110:111], v[110:111], v[220:221] op_sel_hi:[1,0]
	v_pk_mul_f32 v[112:113], v[112:113], v[220:221] op_sel_hi:[1,0]
	v_pk_mul_f32 v[114:115], v[114:115], v[220:221] op_sel_hi:[1,0]
	v_pk_mul_f32 v[116:117], v[116:117], v[220:221] op_sel_hi:[1,0]
	v_pk_fma_f32 v[102:103], v[184:185], v[102:103], v[200:201]
	v_pk_fma_f32 v[104:105], v[186:187], v[104:105], v[202:203]
	v_pk_fma_f32 v[106:107], v[188:189], v[106:107], v[204:205]
	v_pk_fma_f32 v[108:109], v[190:191], v[108:109], v[206:207]
	v_pk_fma_f32 v[110:111], v[192:193], v[110:111], v[226:227]
	v_pk_fma_f32 v[112:113], v[194:195], v[112:113], v[228:229]
	v_pk_fma_f32 v[114:115], v[196:197], v[114:115], v[230:231]
	v_pk_fma_f32 v[116:117], v[198:199], v[116:117], v[232:233]
	global_store_dwordx4 v212, v[102:105], s[50:51] offset:0
	global_store_dwordx4 v212, v[106:109], s[50:51] offset:1024
	global_store_dwordx4 v212, v[110:113], s[50:51] offset:2048
	global_store_dwordx4 v212, v[114:117], s[50:51] offset:3072
	v_cvt_pk_bf16_f32 v102, v102, v103
	v_cvt_pk_bf16_f32 v103, v104, v105
	v_cvt_pk_bf16_f32 v106, v106, v107
	v_cvt_pk_bf16_f32 v107, v108, v109
	v_cvt_pk_bf16_f32 v110, v110, v111
	v_cvt_pk_bf16_f32 v111, v112, v113
	v_cvt_pk_bf16_f32 v114, v114, v115
	v_cvt_pk_bf16_f32 v115, v116, v117
	global_store_dwordx2 v214, v[102:103], s[70:71] offset:0
	global_store_dwordx2 v214, v[106:107], s[70:71] offset:512
	global_store_dwordx2 v214, v[110:111], s[70:71] offset:1024
	global_store_dwordx2 v214, v[114:115], s[70:71] offset:1536
	s_waitcnt vmcnt(48)
	v_pk_add_f32 v[76:77], v[118:119], v[120:121]
	v_pk_add_f32 v[136:137], v[122:123], v[124:125]
	v_pk_add_f32 v[138:139], v[144:145], v[146:147]
	v_pk_add_f32 v[208:209], v[148:149], v[150:151]
	v_pk_add_f32 v[76:77], v[76:77], v[136:137]
	v_pk_add_f32 v[138:139], v[138:139], v[208:209]
	v_pk_add_f32 v[76:77], v[76:77], v[138:139]
	v_add_f32_e32 v131, v76, v77
	s_nop 1
	v_add_f32_dpp v131, v131, v131 quad_perm:[1,0,3,2] row_mask:0xf bank_mask:0xf bound_ctrl:1
	s_nop 1
	v_add_f32_dpp v131, v131, v131 quad_perm:[2,3,0,1] row_mask:0xf bank_mask:0xf bound_ctrl:1
	s_nop 1
	v_add_f32_dpp v131, v131, v131 row_half_mirror row_mask:0xf bank_mask:0xf bound_ctrl:1
	s_nop 1
	v_add_f32_dpp v131, v131, v131 row_mirror row_mask:0xf bank_mask:0xf bound_ctrl:1
	s_nop 1
	v_readlane_b32 s56, v131, 0
	v_readlane_b32 s57, v131, 16
	v_readlane_b32 s58, v131, 32
	v_readlane_b32 s59, v131, 48
	v_mov_b32_e32 v222, s57
	v_mov_b32_e32 v223, s59
	v_add_f32_e32 v222, s56, v222
	v_add_f32_e32 v223, s58, v223
	v_add_f32_e32 v131, v222, v223
	v_mul_f32_e32 v216, 0x3a800000, v131
	v_pk_add_f32 v[118:119], v[118:119], v[216:217] op_sel_hi:[1,0] neg_lo:[0,1] neg_hi:[0,1]
	v_pk_add_f32 v[120:121], v[120:121], v[216:217] op_sel_hi:[1,0] neg_lo:[0,1] neg_hi:[0,1]
	v_pk_add_f32 v[122:123], v[122:123], v[216:217] op_sel_hi:[1,0] neg_lo:[0,1] neg_hi:[0,1]
	v_pk_add_f32 v[124:125], v[124:125], v[216:217] op_sel_hi:[1,0] neg_lo:[0,1] neg_hi:[0,1]
	v_pk_add_f32 v[144:145], v[144:145], v[216:217] op_sel_hi:[1,0] neg_lo:[0,1] neg_hi:[0,1]
	v_pk_add_f32 v[146:147], v[146:147], v[216:217] op_sel_hi:[1,0] neg_lo:[0,1] neg_hi:[0,1]
	v_pk_add_f32 v[148:149], v[148:149], v[216:217] op_sel_hi:[1,0] neg_lo:[0,1] neg_hi:[0,1]
	v_pk_add_f32 v[150:151], v[150:151], v[216:217] op_sel_hi:[1,0] neg_lo:[0,1] neg_hi:[0,1]
	v_pk_mul_f32 v[76:77], v[118:119], v[118:119]
	v_pk_mul_f32 v[136:137], v[120:121], v[120:121]
	v_add_f32_e32 v133, v76, v77
	v_add_f32_e32 v133, v136, v133
	v_add_f32_e32 v133, v137, v133
	v_pk_mul_f32 v[76:77], v[122:123], v[122:123]
	v_pk_mul_f32 v[136:137], v[124:125], v[124:125]
	v_add_f32_e32 v133, v76, v133
	v_add_f32_e32 v133, v77, v133
	v_add_f32_e32 v133, v136, v133
	v_add_f32_e32 v133, v137, v133
	v_pk_mul_f32 v[76:77], v[144:145], v[144:145]
	v_pk_mul_f32 v[136:137], v[146:147], v[146:147]
	v_add_f32_e32 v133, v76, v133
	v_add_f32_e32 v133, v77, v133
	v_add_f32_e32 v133, v136, v133
	v_add_f32_e32 v133, v137, v133
	v_pk_mul_f32 v[76:77], v[148:149], v[148:149]
	v_pk_mul_f32 v[136:137], v[150:151], v[150:151]
	v_add_f32_e32 v133, v76, v133
	v_add_f32_e32 v133, v77, v133
	v_add_f32_e32 v133, v136, v133
	v_add_f32_e32 v133, v137, v133
	s_nop 1
	v_add_f32_dpp v133, v133, v133 quad_perm:[1,0,3,2] row_mask:0xf bank_mask:0xf bound_ctrl:1
	s_nop 1
	v_add_f32_dpp v133, v133, v133 quad_perm:[2,3,0,1] row_mask:0xf bank_mask:0xf bound_ctrl:1
	s_nop 1
	v_add_f32_dpp v133, v133, v133 row_half_mirror row_mask:0xf bank_mask:0xf bound_ctrl:1
	s_nop 1
	v_add_f32_dpp v133, v133, v133 row_mirror row_mask:0xf bank_mask:0xf bound_ctrl:1
	s_nop 1
	v_readlane_b32 s56, v133, 0
	v_readlane_b32 s57, v133, 16
	v_readlane_b32 s58, v133, 32
	v_readlane_b32 s59, v133, 48
	v_mov_b32_e32 v222, s57
	v_mov_b32_e32 v223, s59
	v_add_f32_e32 v222, s56, v222
	v_add_f32_e32 v223, s58, v223
	v_add_f32_e32 v133, v222, v223
	v_fmamk_f32 v133, v133, 0x3a800000, v215
	v_cmp_gt_f32_e32 vcc, s33, v133
	v_mul_f32_e32 v222, 0x4b800000, v133
	s_nop 0
	v_cndmask_b32_e32 v133, v133, v222, vcc
	v_rsq_f32_e32 v133, v133
	s_nop 0
	v_mul_f32_e32 v222, 0x45800000, v133
	v_cndmask_b32_e32 v220, v133, v222, vcc
	v_pk_mul_f32 v[118:119], v[118:119], v[220:221] op_sel_hi:[1,0]
	v_pk_mul_f32 v[120:121], v[120:121], v[220:221] op_sel_hi:[1,0]
	v_pk_mul_f32 v[122:123], v[122:123], v[220:221] op_sel_hi:[1,0]
	v_pk_mul_f32 v[124:125], v[124:125], v[220:221] op_sel_hi:[1,0]
	v_pk_mul_f32 v[144:145], v[144:145], v[220:221] op_sel_hi:[1,0]
	v_pk_mul_f32 v[146:147], v[146:147], v[220:221] op_sel_hi:[1,0]
	v_pk_mul_f32 v[148:149], v[148:149], v[220:221] op_sel_hi:[1,0]
	v_pk_mul_f32 v[150:151], v[150:151], v[220:221] op_sel_hi:[1,0]
	v_pk_fma_f32 v[118:119], v[184:185], v[118:119], v[200:201]
	v_pk_fma_f32 v[120:121], v[186:187], v[120:121], v[202:203]
	v_pk_fma_f32 v[122:123], v[188:189], v[122:123], v[204:205]
	v_pk_fma_f32 v[124:125], v[190:191], v[124:125], v[206:207]
	v_pk_fma_f32 v[144:145], v[192:193], v[144:145], v[226:227]
	v_pk_fma_f32 v[146:147], v[194:195], v[146:147], v[228:229]
	v_pk_fma_f32 v[148:149], v[196:197], v[148:149], v[230:231]
	v_pk_fma_f32 v[150:151], v[198:199], v[150:151], v[232:233]
	global_store_dwordx4 v212, v[118:121], s[52:53] offset:0
	global_store_dwordx4 v212, v[122:125], s[52:53] offset:1024
	global_store_dwordx4 v212, v[144:147], s[52:53] offset:2048
	global_store_dwordx4 v212, v[148:151], s[52:53] offset:3072
	v_cvt_pk_bf16_f32 v118, v118, v119
	v_cvt_pk_bf16_f32 v119, v120, v121
	v_cvt_pk_bf16_f32 v122, v122, v123
	v_cvt_pk_bf16_f32 v123, v124, v125
	v_cvt_pk_bf16_f32 v144, v144, v145
	v_cvt_pk_bf16_f32 v145, v146, v147
	v_cvt_pk_bf16_f32 v148, v148, v149
	v_cvt_pk_bf16_f32 v149, v150, v151
	global_store_dwordx2 v214, v[118:119], s[70:71] offset:2048
	global_store_dwordx2 v214, v[122:123], s[70:71] offset:2560
	global_store_dwordx2 v214, v[144:145], s[70:71] offset:3072
	global_store_dwordx2 v214, v[148:149], s[70:71] offset:3584
	s_waitcnt vmcnt(52)
	v_pk_add_f32 v[76:77], v[152:153], v[154:155]
	v_pk_add_f32 v[136:137], v[156:157], v[158:159]
	v_pk_add_f32 v[138:139], v[160:161], v[162:163]
	v_pk_add_f32 v[208:209], v[164:165], v[166:167]
	v_pk_add_f32 v[76:77], v[76:77], v[136:137]
	v_pk_add_f32 v[138:139], v[138:139], v[208:209]
	v_pk_add_f32 v[76:77], v[76:77], v[138:139]
	v_add_f32_e32 v131, v76, v77
	s_nop 1
	v_add_f32_dpp v131, v131, v131 quad_perm:[1,0,3,2] row_mask:0xf bank_mask:0xf bound_ctrl:1
	s_nop 1
	v_add_f32_dpp v131, v131, v131 quad_perm:[2,3,0,1] row_mask:0xf bank_mask:0xf bound_ctrl:1
	s_nop 1
	v_add_f32_dpp v131, v131, v131 row_half_mirror row_mask:0xf bank_mask:0xf bound_ctrl:1
	s_nop 1
	v_add_f32_dpp v131, v131, v131 row_mirror row_mask:0xf bank_mask:0xf bound_ctrl:1
	s_nop 1
	v_readlane_b32 s56, v131, 0
	v_readlane_b32 s57, v131, 16
	v_readlane_b32 s58, v131, 32
	v_readlane_b32 s59, v131, 48
	v_mov_b32_e32 v222, s57
	v_mov_b32_e32 v223, s59
	v_add_f32_e32 v222, s56, v222
	v_add_f32_e32 v223, s58, v223
	v_add_f32_e32 v131, v222, v223
	v_mul_f32_e32 v216, 0x3a800000, v131
	v_pk_add_f32 v[152:153], v[152:153], v[216:217] op_sel_hi:[1,0] neg_lo:[0,1] neg_hi:[0,1]
	v_pk_add_f32 v[154:155], v[154:155], v[216:217] op_sel_hi:[1,0] neg_lo:[0,1] neg_hi:[0,1]
	v_pk_add_f32 v[156:157], v[156:157], v[216:217] op_sel_hi:[1,0] neg_lo:[0,1] neg_hi:[0,1]
	v_pk_add_f32 v[158:159], v[158:159], v[216:217] op_sel_hi:[1,0] neg_lo:[0,1] neg_hi:[0,1]
	v_pk_add_f32 v[160:161], v[160:161], v[216:217] op_sel_hi:[1,0] neg_lo:[0,1] neg_hi:[0,1]
	v_pk_add_f32 v[162:163], v[162:163], v[216:217] op_sel_hi:[1,0] neg_lo:[0,1] neg_hi:[0,1]
	v_pk_add_f32 v[164:165], v[164:165], v[216:217] op_sel_hi:[1,0] neg_lo:[0,1] neg_hi:[0,1]
	v_pk_add_f32 v[166:167], v[166:167], v[216:217] op_sel_hi:[1,0] neg_lo:[0,1] neg_hi:[0,1]
	v_pk_mul_f32 v[76:77], v[152:153], v[152:153]
	v_pk_mul_f32 v[136:137], v[154:155], v[154:155]
	v_add_f32_e32 v133, v76, v77
	v_add_f32_e32 v133, v136, v133
	v_add_f32_e32 v133, v137, v133
	v_pk_mul_f32 v[76:77], v[156:157], v[156:157]
	v_pk_mul_f32 v[136:137], v[158:159], v[158:159]
	v_add_f32_e32 v133, v76, v133
	v_add_f32_e32 v133, v77, v133
	v_add_f32_e32 v133, v136, v133
	v_add_f32_e32 v133, v137, v133
	v_pk_mul_f32 v[76:77], v[160:161], v[160:161]
	v_pk_mul_f32 v[136:137], v[162:163], v[162:163]
	v_add_f32_e32 v133, v76, v133
	v_add_f32_e32 v133, v77, v133
	v_add_f32_e32 v133, v136, v133
	v_add_f32_e32 v133, v137, v133
	v_pk_mul_f32 v[76:77], v[164:165], v[164:165]
	v_pk_mul_f32 v[136:137], v[166:167], v[166:167]
	v_add_f32_e32 v133, v76, v133
	v_add_f32_e32 v133, v77, v133
	v_add_f32_e32 v133, v136, v133
	v_add_f32_e32 v133, v137, v133
	s_nop 1
	v_add_f32_dpp v133, v133, v133 quad_perm:[1,0,3,2] row_mask:0xf bank_mask:0xf bound_ctrl:1
	s_nop 1
	v_add_f32_dpp v133, v133, v133 quad_perm:[2,3,0,1] row_mask:0xf bank_mask:0xf bound_ctrl:1
	s_nop 1
	v_add_f32_dpp v133, v133, v133 row_half_mirror row_mask:0xf bank_mask:0xf bound_ctrl:1
	s_nop 1
	v_add_f32_dpp v133, v133, v133 row_mirror row_mask:0xf bank_mask:0xf bound_ctrl:1
	s_nop 1
	v_readlane_b32 s56, v133, 0
	v_readlane_b32 s57, v133, 16
	v_readlane_b32 s58, v133, 32
	v_readlane_b32 s59, v133, 48
	v_mov_b32_e32 v222, s57
	v_mov_b32_e32 v223, s59
	v_add_f32_e32 v222, s56, v222
	v_add_f32_e32 v223, s58, v223
	v_add_f32_e32 v133, v222, v223
	v_fmamk_f32 v133, v133, 0x3a800000, v215
	v_cmp_gt_f32_e32 vcc, s33, v133
	v_mul_f32_e32 v222, 0x4b800000, v133
	s_nop 0
	v_cndmask_b32_e32 v133, v133, v222, vcc
	v_rsq_f32_e32 v133, v133
	s_nop 0
	v_mul_f32_e32 v222, 0x45800000, v133
	v_cndmask_b32_e32 v220, v133, v222, vcc
	v_pk_mul_f32 v[152:153], v[152:153], v[220:221] op_sel_hi:[1,0]
	v_pk_mul_f32 v[154:155], v[154:155], v[220:221] op_sel_hi:[1,0]
	v_pk_mul_f32 v[156:157], v[156:157], v[220:221] op_sel_hi:[1,0]
	v_pk_mul_f32 v[158:159], v[158:159], v[220:221] op_sel_hi:[1,0]
	v_pk_mul_f32 v[160:161], v[160:161], v[220:221] op_sel_hi:[1,0]
	v_pk_mul_f32 v[162:163], v[162:163], v[220:221] op_sel_hi:[1,0]
	v_pk_mul_f32 v[164:165], v[164:165], v[220:221] op_sel_hi:[1,0]
	v_pk_mul_f32 v[166:167], v[166:167], v[220:221] op_sel_hi:[1,0]
	v_pk_fma_f32 v[152:153], v[184:185], v[152:153], v[200:201]
	v_pk_fma_f32 v[154:155], v[186:187], v[154:155], v[202:203]
	v_pk_fma_f32 v[156:157], v[188:189], v[156:157], v[204:205]
	v_pk_fma_f32 v[158:159], v[190:191], v[158:159], v[206:207]
	v_pk_fma_f32 v[160:161], v[192:193], v[160:161], v[226:227]
	v_pk_fma_f32 v[162:163], v[194:195], v[162:163], v[228:229]
	v_pk_fma_f32 v[164:165], v[196:197], v[164:165], v[230:231]
	v_pk_fma_f32 v[166:167], v[198:199], v[166:167], v[232:233]
	global_store_dwordx4 v212, v[152:155], s[62:63] offset:0
	global_store_dwordx4 v212, v[156:159], s[62:63] offset:1024
	global_store_dwordx4 v212, v[160:163], s[62:63] offset:2048
	global_store_dwordx4 v212, v[164:167], s[62:63] offset:3072
	v_cvt_pk_bf16_f32 v152, v152, v153
	v_cvt_pk_bf16_f32 v153, v154, v155
	v_cvt_pk_bf16_f32 v156, v156, v157
	v_cvt_pk_bf16_f32 v157, v158, v159
	v_cvt_pk_bf16_f32 v160, v160, v161
	v_cvt_pk_bf16_f32 v161, v162, v163
	v_cvt_pk_bf16_f32 v164, v164, v165
	v_cvt_pk_bf16_f32 v165, v166, v167
	global_store_dwordx2 v214, v[152:153], s[72:73] offset:0
	global_store_dwordx2 v214, v[156:157], s[72:73] offset:512
	global_store_dwordx2 v214, v[160:161], s[72:73] offset:1024
	global_store_dwordx2 v214, v[164:165], s[72:73] offset:1536
	s_waitcnt vmcnt(56)
	v_pk_add_f32 v[76:77], v[168:169], v[170:171]
	v_pk_add_f32 v[136:137], v[172:173], v[174:175]
	v_pk_add_f32 v[138:139], v[176:177], v[178:179]
	v_pk_add_f32 v[208:209], v[180:181], v[182:183]
	v_pk_add_f32 v[76:77], v[76:77], v[136:137]
	v_pk_add_f32 v[138:139], v[138:139], v[208:209]
	v_pk_add_f32 v[76:77], v[76:77], v[138:139]
	v_add_f32_e32 v131, v76, v77
	s_nop 1
	v_add_f32_dpp v131, v131, v131 quad_perm:[1,0,3,2] row_mask:0xf bank_mask:0xf bound_ctrl:1
	s_nop 1
	v_add_f32_dpp v131, v131, v131 quad_perm:[2,3,0,1] row_mask:0xf bank_mask:0xf bound_ctrl:1
	s_nop 1
	v_add_f32_dpp v131, v131, v131 row_half_mirror row_mask:0xf bank_mask:0xf bound_ctrl:1
	s_nop 1
	v_add_f32_dpp v131, v131, v131 row_mirror row_mask:0xf bank_mask:0xf bound_ctrl:1
	s_nop 1
	v_readlane_b32 s56, v131, 0
	v_readlane_b32 s57, v131, 16
	v_readlane_b32 s58, v131, 32
	v_readlane_b32 s59, v131, 48
	v_mov_b32_e32 v222, s57
	v_mov_b32_e32 v223, s59
	v_add_f32_e32 v222, s56, v222
	v_add_f32_e32 v223, s58, v223
	v_add_f32_e32 v131, v222, v223
	v_mul_f32_e32 v216, 0x3a800000, v131
	v_pk_add_f32 v[168:169], v[168:169], v[216:217] op_sel_hi:[1,0] neg_lo:[0,1] neg_hi:[0,1]
	v_pk_add_f32 v[170:171], v[170:171], v[216:217] op_sel_hi:[1,0] neg_lo:[0,1] neg_hi:[0,1]
	v_pk_add_f32 v[172:173], v[172:173], v[216:217] op_sel_hi:[1,0] neg_lo:[0,1] neg_hi:[0,1]
	v_pk_add_f32 v[174:175], v[174:175], v[216:217] op_sel_hi:[1,0] neg_lo:[0,1] neg_hi:[0,1]
	v_pk_add_f32 v[176:177], v[176:177], v[216:217] op_sel_hi:[1,0] neg_lo:[0,1] neg_hi:[0,1]
	v_pk_add_f32 v[178:179], v[178:179], v[216:217] op_sel_hi:[1,0] neg_lo:[0,1] neg_hi:[0,1]
	v_pk_add_f32 v[180:181], v[180:181], v[216:217] op_sel_hi:[1,0] neg_lo:[0,1] neg_hi:[0,1]
	v_pk_add_f32 v[182:183], v[182:183], v[216:217] op_sel_hi:[1,0] neg_lo:[0,1] neg_hi:[0,1]
	v_pk_mul_f32 v[76:77], v[168:169], v[168:169]
	v_pk_mul_f32 v[136:137], v[170:171], v[170:171]
	v_add_f32_e32 v133, v76, v77
	v_add_f32_e32 v133, v136, v133
	v_add_f32_e32 v133, v137, v133
	v_pk_mul_f32 v[76:77], v[172:173], v[172:173]
	v_pk_mul_f32 v[136:137], v[174:175], v[174:175]
	v_add_f32_e32 v133, v76, v133
	v_add_f32_e32 v133, v77, v133
	v_add_f32_e32 v133, v136, v133
	v_add_f32_e32 v133, v137, v133
	v_pk_mul_f32 v[76:77], v[176:177], v[176:177]
	v_pk_mul_f32 v[136:137], v[178:179], v[178:179]
	v_add_f32_e32 v133, v76, v133
	v_add_f32_e32 v133, v77, v133
	v_add_f32_e32 v133, v136, v133
	v_add_f32_e32 v133, v137, v133
	v_pk_mul_f32 v[76:77], v[180:181], v[180:181]
	v_pk_mul_f32 v[136:137], v[182:183], v[182:183]
	v_add_f32_e32 v133, v76, v133
	v_add_f32_e32 v133, v77, v133
	v_add_f32_e32 v133, v136, v133
	v_add_f32_e32 v133, v137, v133
	s_nop 1
	v_add_f32_dpp v133, v133, v133 quad_perm:[1,0,3,2] row_mask:0xf bank_mask:0xf bound_ctrl:1
	s_nop 1
	v_add_f32_dpp v133, v133, v133 quad_perm:[2,3,0,1] row_mask:0xf bank_mask:0xf bound_ctrl:1
	s_nop 1
	v_add_f32_dpp v133, v133, v133 row_half_mirror row_mask:0xf bank_mask:0xf bound_ctrl:1
	s_nop 1
	v_add_f32_dpp v133, v133, v133 row_mirror row_mask:0xf bank_mask:0xf bound_ctrl:1
	s_nop 1
	v_readlane_b32 s56, v133, 0
	v_readlane_b32 s57, v133, 16
	v_readlane_b32 s58, v133, 32
	v_readlane_b32 s59, v133, 48
	v_mov_b32_e32 v222, s57
	v_mov_b32_e32 v223, s59
	v_add_f32_e32 v222, s56, v222
	v_add_f32_e32 v223, s58, v223
	v_add_f32_e32 v133, v222, v223
	v_fmamk_f32 v133, v133, 0x3a800000, v215
	v_cmp_gt_f32_e32 vcc, s33, v133
	v_mul_f32_e32 v222, 0x4b800000, v133
	s_nop 0
	v_cndmask_b32_e32 v133, v133, v222, vcc
	v_rsq_f32_e32 v133, v133
	s_nop 0
	v_mul_f32_e32 v222, 0x45800000, v133
	v_cndmask_b32_e32 v220, v133, v222, vcc
	v_pk_mul_f32 v[168:169], v[168:169], v[220:221] op_sel_hi:[1,0]
	v_pk_mul_f32 v[170:171], v[170:171], v[220:221] op_sel_hi:[1,0]
	v_pk_mul_f32 v[172:173], v[172:173], v[220:221] op_sel_hi:[1,0]
	v_pk_mul_f32 v[174:175], v[174:175], v[220:221] op_sel_hi:[1,0]
	v_pk_mul_f32 v[176:177], v[176:177], v[220:221] op_sel_hi:[1,0]
	v_pk_mul_f32 v[178:179], v[178:179], v[220:221] op_sel_hi:[1,0]
	v_pk_mul_f32 v[180:181], v[180:181], v[220:221] op_sel_hi:[1,0]
	v_pk_mul_f32 v[182:183], v[182:183], v[220:221] op_sel_hi:[1,0]
	v_pk_fma_f32 v[168:169], v[184:185], v[168:169], v[200:201]
	v_pk_fma_f32 v[170:171], v[186:187], v[170:171], v[202:203]
	v_pk_fma_f32 v[172:173], v[188:189], v[172:173], v[204:205]
	v_pk_fma_f32 v[174:175], v[190:191], v[174:175], v[206:207]
	v_pk_fma_f32 v[176:177], v[192:193], v[176:177], v[226:227]
	v_pk_fma_f32 v[178:179], v[194:195], v[178:179], v[228:229]
	v_pk_fma_f32 v[180:181], v[196:197], v[180:181], v[230:231]
	v_pk_fma_f32 v[182:183], v[198:199], v[182:183], v[232:233]
	global_store_dwordx4 v212, v[168:171], s[64:65] offset:0
	global_store_dwordx4 v212, v[172:175], s[64:65] offset:1024
	global_store_dwordx4 v212, v[176:179], s[64:65] offset:2048
	global_store_dwordx4 v212, v[180:183], s[64:65] offset:3072
	v_cvt_pk_bf16_f32 v168, v168, v169
	v_cvt_pk_bf16_f32 v169, v170, v171
	v_cvt_pk_bf16_f32 v172, v172, v173
	v_cvt_pk_bf16_f32 v173, v174, v175
	v_cvt_pk_bf16_f32 v176, v176, v177
	v_cvt_pk_bf16_f32 v177, v178, v179
	v_cvt_pk_bf16_f32 v180, v180, v181
	v_cvt_pk_bf16_f32 v181, v182, v183
	global_store_dwordx2 v214, v[168:169], s[72:73] offset:2048
	global_store_dwordx2 v214, v[172:173], s[72:73] offset:2560
	global_store_dwordx2 v214, v[176:177], s[72:73] offset:3072
	global_store_dwordx2 v214, v[180:181], s[72:73] offset:3584
	s_xor_b64 s[20:21], exec, -1
	s_branch .LBB0_1609
